# SWIGLU GEMMs: 256x128 block tile (two m-tiles share each weight slab), single LDS stage, own epilogue
# speedup vs baseline: 1.4351x; 1.0169x over previous
.LBB0_139:
	s_sub_u32 s4, s0, s65
	s_lshl_b32 s4, s4, 8
	s_lshl_b32 s15, s65, 7
	s_add_u32 s14, s4, s15
	v_lshrrev_b32_e32 v238, 4, v182
	v_xor_b32_e32 v238, v238, v182
	v_and_b32_e32 v238, 7, v238
	v_lshlrev_b32_e32 v238, 4, v238
	v_lshrrev_b32_e32 v239, 3, v182
	v_lshrrev_b32_e32 v240, 6, v182
	v_lshl_or_b32 v224, v239, 11, v238
	v_readfirstlane_b32 s5, v240
	v_add_u32_e32 v225, 0x10000, v224
	v_add_u32_e32 v226, 0x20000, v224
	v_add_u32_e32 v227, 0x30000, v224
	v_add_u32_e32 v228, 0x40000, v224
	v_add_u32_e32 v229, 0x50000, v224
	v_add_u32_e32 v230, 0x60000, v224
	v_add_u32_e32 v231, 0x70000, v224
	v_and_b32_e32 v241, 15, v182
	v_bfe_u32 v242, v182, 4, 2
	v_bfe_u32 v243, v182, 1, 3
	v_xor_b32_e32 v244, v242, v243
	v_or_b32_e32 v245, 4, v242
	v_xor_b32_e32 v245, v245, v243
	v_lshlrev_b32_e32 v244, 4, v244
	v_lshlrev_b32_e32 v245, 4, v245
	v_lshl_or_b32 v244, v241, 7, v244
	v_lshl_or_b32 v245, v241, 7, v245
	v_bfe_u32 v246, v182, 7, 1
	v_bfe_u32 v247, v182, 6, 1
	v_lshl_add_u32 v233, v246, 14, v244
	v_lshl_add_u32 v234, v246, 14, v245
	v_lshl_add_u32 v235, v247, 13, v244
	v_lshl_add_u32 v236, v247, 13, v245
	v_lshlrev_b32_e32 v248, 2, v242
	v_lshl_or_b32 v248, v246, 7, v248
	v_mul_u32_u24_e32 v237, 0x1600, v248
	v_lshl_or_b32 v248, v247, 5, v241
	v_lshl_add_u32 v237, v248, 1, v237
	s_lshl_b32 s5, s5, 10
	s_lshl_b32 s4, s14, 11
	s_add_u32 s8, s40, s4
	s_addc_u32 s9, s41, 0
	s_lshl_b32 s4, s13, 18
	s_add_u32 s10, s66, s4
	s_addc_u32 s11, s67, 0
	s_mul_i32 s4, s14, 0x1600
	s_lshl_b32 s15, s13, 7
	s_add_u32 s4, s4, s15
	s_add_u32 s98, s30, s4
	s_addc_u32 s99, s31, 0
	v_mov_b32_e32 v0, 0
	v_mov_b32_e32 v1, v0
	v_mov_b32_e32 v2, v0
	v_mov_b32_e32 v3, v0
	v_mov_b32_e32 v4, v0
	v_mov_b32_e32 v5, v0
	v_mov_b32_e32 v6, v0
	v_mov_b32_e32 v7, v0
	v_mov_b32_e32 v8, v0
	v_mov_b32_e32 v9, v0
	v_mov_b32_e32 v10, v0
	v_mov_b32_e32 v11, v0
	v_mov_b32_e32 v12, v0
	v_mov_b32_e32 v13, v0
	v_mov_b32_e32 v14, v0
	v_mov_b32_e32 v15, v0
	v_mov_b32_e32 v16, v0
	v_mov_b32_e32 v17, v0
	v_mov_b32_e32 v18, v0
	v_mov_b32_e32 v19, v0
	v_mov_b32_e32 v20, v0
	v_mov_b32_e32 v21, v0
	v_mov_b32_e32 v22, v0
	v_mov_b32_e32 v23, v0
	v_mov_b32_e32 v24, v0
	v_mov_b32_e32 v25, v0
	v_mov_b32_e32 v26, v0
	v_mov_b32_e32 v27, v0
	v_mov_b32_e32 v28, v0
	v_mov_b32_e32 v29, v0
	v_mov_b32_e32 v30, v0
	v_mov_b32_e32 v31, v0
	v_mov_b32_e32 v32, v0
	v_mov_b32_e32 v33, v0
	v_mov_b32_e32 v34, v0
	v_mov_b32_e32 v35, v0
	v_mov_b32_e32 v36, v0
	v_mov_b32_e32 v37, v0
	v_mov_b32_e32 v38, v0
	v_mov_b32_e32 v39, v0
	v_mov_b32_e32 v40, v0
	v_mov_b32_e32 v41, v0
	v_mov_b32_e32 v42, v0
	v_mov_b32_e32 v43, v0
	v_mov_b32_e32 v44, v0
	v_mov_b32_e32 v45, v0
	v_mov_b32_e32 v46, v0
	v_mov_b32_e32 v47, v0
	v_mov_b32_e32 v48, v0
	v_mov_b32_e32 v49, v0
	v_mov_b32_e32 v50, v0
	v_mov_b32_e32 v51, v0
	v_mov_b32_e32 v52, v0
	v_mov_b32_e32 v53, v0
	v_mov_b32_e32 v54, v0
	v_mov_b32_e32 v55, v0
	v_mov_b32_e32 v56, v0
	v_mov_b32_e32 v57, v0
	v_mov_b32_e32 v58, v0
	v_mov_b32_e32 v59, v0
	v_mov_b32_e32 v60, v0
	v_mov_b32_e32 v61, v0
	v_mov_b32_e32 v62, v0
	v_mov_b32_e32 v63, v0
	v_mov_b32_e32 v64, v0
	v_mov_b32_e32 v65, v0
	v_mov_b32_e32 v66, v0
	v_mov_b32_e32 v67, v0
	v_mov_b32_e32 v68, v0
	v_mov_b32_e32 v69, v0
	v_mov_b32_e32 v70, v0
	v_mov_b32_e32 v71, v0
	v_mov_b32_e32 v72, v0
	v_mov_b32_e32 v73, v0
	v_mov_b32_e32 v74, v0
	v_mov_b32_e32 v75, v0
	v_mov_b32_e32 v76, v0
	v_mov_b32_e32 v77, v0
	v_mov_b32_e32 v78, v0
	v_mov_b32_e32 v79, v0
	v_mov_b32_e32 v80, v0
	v_mov_b32_e32 v81, v0
	v_mov_b32_e32 v82, v0
	v_mov_b32_e32 v83, v0
	v_mov_b32_e32 v84, v0
	v_mov_b32_e32 v85, v0
	v_mov_b32_e32 v86, v0
	v_mov_b32_e32 v87, v0
	v_mov_b32_e32 v88, v0
	v_mov_b32_e32 v89, v0
	v_mov_b32_e32 v90, v0
	v_mov_b32_e32 v91, v0
	v_mov_b32_e32 v92, v0
	v_mov_b32_e32 v93, v0
	v_mov_b32_e32 v94, v0
	v_mov_b32_e32 v95, v0
	v_mov_b32_e32 v96, v0
	v_mov_b32_e32 v97, v0
	v_mov_b32_e32 v98, v0
	v_mov_b32_e32 v99, v0
	v_mov_b32_e32 v100, v0
	v_mov_b32_e32 v101, v0
	v_mov_b32_e32 v102, v0
	v_mov_b32_e32 v103, v0
	v_mov_b32_e32 v104, v0
	v_mov_b32_e32 v105, v0
	v_mov_b32_e32 v106, v0
	v_mov_b32_e32 v107, v0
	v_mov_b32_e32 v108, v0
	v_mov_b32_e32 v109, v0
	v_mov_b32_e32 v110, v0
	v_mov_b32_e32 v111, v0
	v_mov_b32_e32 v116, v0
	v_mov_b32_e32 v117, v0
	v_mov_b32_e32 v118, v0
	v_mov_b32_e32 v119, v0
	v_mov_b32_e32 v120, v0
	v_mov_b32_e32 v121, v0
	v_mov_b32_e32 v122, v0
	v_mov_b32_e32 v123, v0
	v_mov_b32_e32 v124, v0
	v_mov_b32_e32 v125, v0
	v_mov_b32_e32 v126, v0
	v_mov_b32_e32 v127, v0
	v_mov_b32_e32 v128, v0
	v_mov_b32_e32 v129, v0
	v_mov_b32_e32 v130, v0
	v_mov_b32_e32 v131, v0
	s_movk_i32 s16, 16
.Lg3_sw1:
	s_barrier
	s_add_u32 m0, s5, 0x0
	s_nop 0
	global_load_lds_dwordx4 v224, s[8:9]
	s_add_u32 m0, s5, 0x1000
	s_nop 0
	global_load_lds_dwordx4 v225, s[8:9]
	s_add_u32 m0, s5, 0x2000
	s_nop 0
	global_load_lds_dwordx4 v226, s[8:9]
	s_add_u32 m0, s5, 0x3000
	s_nop 0
	global_load_lds_dwordx4 v227, s[8:9]
	s_add_u32 m0, s5, 0x4000
	s_nop 0
	global_load_lds_dwordx4 v228, s[8:9]
	s_add_u32 m0, s5, 0x5000
	s_nop 0
	global_load_lds_dwordx4 v229, s[8:9]
	s_add_u32 m0, s5, 0x6000
	s_nop 0
	global_load_lds_dwordx4 v230, s[8:9]
	s_add_u32 m0, s5, 0x7000
	s_nop 0
	global_load_lds_dwordx4 v231, s[8:9]
	s_add_u32 m0, s5, 0x8000
	s_nop 0
	global_load_lds_dwordx4 v224, s[10:11]
	s_add_u32 m0, s5, 0x9000
	s_nop 0
	global_load_lds_dwordx4 v225, s[10:11]
	s_add_u32 m0, s5, 0xa000
	s_nop 0
	global_load_lds_dwordx4 v226, s[10:11]
	s_add_u32 m0, s5, 0xb000
	s_nop 0
	global_load_lds_dwordx4 v227, s[10:11]
	s_add_u32 s8, s8, 0x80
	s_addc_u32 s9, s9, 0
	s_add_u32 s10, s10, 0x80
	s_addc_u32 s11, s11, 0
	s_waitcnt vmcnt(0)
	s_barrier
	ds_read_b128 v[164:167], v235 offset:32768
	ds_read_b128 v[168:171], v235 offset:34816
	ds_read_b128 v[172:175], v235 offset:36864
	ds_read_b128 v[176:179], v235 offset:38912
	ds_read_b128 v[132:135], v233 offset:0
	ds_read_b128 v[136:139], v233 offset:2048
	ds_read_b128 v[140:143], v233 offset:4096
	ds_read_b128 v[144:147], v233 offset:6144
	ds_read_b128 v[148:151], v233 offset:8192
	ds_read_b128 v[152:155], v233 offset:10240
	ds_read_b128 v[156:159], v233 offset:12288
	ds_read_b128 v[160:163], v233 offset:14336
	s_waitcnt lgkmcnt(7)
	v_mfma_f32_16x16x32_f16 v[0:3], v[132:135], v[164:167], v[0:3]
	v_mfma_f32_16x16x32_f16 v[4:7], v[132:135], v[168:171], v[4:7]
	v_mfma_f32_16x16x32_f16 v[8:11], v[132:135], v[172:175], v[8:11]
	v_mfma_f32_16x16x32_f16 v[12:15], v[132:135], v[176:179], v[12:15]
	s_waitcnt lgkmcnt(6)
	v_mfma_f32_16x16x32_f16 v[16:19], v[136:139], v[164:167], v[16:19]
	v_mfma_f32_16x16x32_f16 v[20:23], v[136:139], v[168:171], v[20:23]
	v_mfma_f32_16x16x32_f16 v[24:27], v[136:139], v[172:175], v[24:27]
	v_mfma_f32_16x16x32_f16 v[28:31], v[136:139], v[176:179], v[28:31]
	s_waitcnt lgkmcnt(5)
	v_mfma_f32_16x16x32_f16 v[32:35], v[140:143], v[164:167], v[32:35]
	v_mfma_f32_16x16x32_f16 v[36:39], v[140:143], v[168:171], v[36:39]
	v_mfma_f32_16x16x32_f16 v[40:43], v[140:143], v[172:175], v[40:43]
	v_mfma_f32_16x16x32_f16 v[44:47], v[140:143], v[176:179], v[44:47]
	s_waitcnt lgkmcnt(4)
	v_mfma_f32_16x16x32_f16 v[48:51], v[144:147], v[164:167], v[48:51]
	v_mfma_f32_16x16x32_f16 v[52:55], v[144:147], v[168:171], v[52:55]
	v_mfma_f32_16x16x32_f16 v[56:59], v[144:147], v[172:175], v[56:59]
	v_mfma_f32_16x16x32_f16 v[60:63], v[144:147], v[176:179], v[60:63]
	s_waitcnt lgkmcnt(3)
	v_mfma_f32_16x16x32_f16 v[64:67], v[148:151], v[164:167], v[64:67]
	v_mfma_f32_16x16x32_f16 v[68:71], v[148:151], v[168:171], v[68:71]
	v_mfma_f32_16x16x32_f16 v[72:75], v[148:151], v[172:175], v[72:75]
	v_mfma_f32_16x16x32_f16 v[76:79], v[148:151], v[176:179], v[76:79]
	s_waitcnt lgkmcnt(2)
	v_mfma_f32_16x16x32_f16 v[80:83], v[152:155], v[164:167], v[80:83]
	v_mfma_f32_16x16x32_f16 v[84:87], v[152:155], v[168:171], v[84:87]
	v_mfma_f32_16x16x32_f16 v[88:91], v[152:155], v[172:175], v[88:91]
	v_mfma_f32_16x16x32_f16 v[92:95], v[152:155], v[176:179], v[92:95]
	s_waitcnt lgkmcnt(1)
	v_mfma_f32_16x16x32_f16 v[96:99], v[156:159], v[164:167], v[96:99]
	v_mfma_f32_16x16x32_f16 v[100:103], v[156:159], v[168:171], v[100:103]
	v_mfma_f32_16x16x32_f16 v[104:107], v[156:159], v[172:175], v[104:107]
	v_mfma_f32_16x16x32_f16 v[108:111], v[156:159], v[176:179], v[108:111]
	s_waitcnt lgkmcnt(0)
	v_mfma_f32_16x16x32_f16 v[116:119], v[160:163], v[164:167], v[116:119]
	v_mfma_f32_16x16x32_f16 v[120:123], v[160:163], v[168:171], v[120:123]
	v_mfma_f32_16x16x32_f16 v[124:127], v[160:163], v[172:175], v[124:127]
	v_mfma_f32_16x16x32_f16 v[128:131], v[160:163], v[176:179], v[128:131]
	ds_read_b128 v[164:167], v236 offset:32768
	ds_read_b128 v[168:171], v236 offset:34816
	ds_read_b128 v[172:175], v236 offset:36864
	ds_read_b128 v[176:179], v236 offset:38912
	ds_read_b128 v[132:135], v234 offset:0
	ds_read_b128 v[136:139], v234 offset:2048
	ds_read_b128 v[140:143], v234 offset:4096
	ds_read_b128 v[144:147], v234 offset:6144
	ds_read_b128 v[148:151], v234 offset:8192
	ds_read_b128 v[152:155], v234 offset:10240
	ds_read_b128 v[156:159], v234 offset:12288
	ds_read_b128 v[160:163], v234 offset:14336
	s_waitcnt lgkmcnt(7)
	v_mfma_f32_16x16x32_f16 v[0:3], v[132:135], v[164:167], v[0:3]
	v_mfma_f32_16x16x32_f16 v[4:7], v[132:135], v[168:171], v[4:7]
	v_mfma_f32_16x16x32_f16 v[8:11], v[132:135], v[172:175], v[8:11]
	v_mfma_f32_16x16x32_f16 v[12:15], v[132:135], v[176:179], v[12:15]
	s_waitcnt lgkmcnt(6)
	v_mfma_f32_16x16x32_f16 v[16:19], v[136:139], v[164:167], v[16:19]
	v_mfma_f32_16x16x32_f16 v[20:23], v[136:139], v[168:171], v[20:23]
	v_mfma_f32_16x16x32_f16 v[24:27], v[136:139], v[172:175], v[24:27]
	v_mfma_f32_16x16x32_f16 v[28:31], v[136:139], v[176:179], v[28:31]
	s_waitcnt lgkmcnt(5)
	v_mfma_f32_16x16x32_f16 v[32:35], v[140:143], v[164:167], v[32:35]
	v_mfma_f32_16x16x32_f16 v[36:39], v[140:143], v[168:171], v[36:39]
	v_mfma_f32_16x16x32_f16 v[40:43], v[140:143], v[172:175], v[40:43]
	v_mfma_f32_16x16x32_f16 v[44:47], v[140:143], v[176:179], v[44:47]
	s_waitcnt lgkmcnt(4)
	v_mfma_f32_16x16x32_f16 v[48:51], v[144:147], v[164:167], v[48:51]
	v_mfma_f32_16x16x32_f16 v[52:55], v[144:147], v[168:171], v[52:55]
	v_mfma_f32_16x16x32_f16 v[56:59], v[144:147], v[172:175], v[56:59]
	v_mfma_f32_16x16x32_f16 v[60:63], v[144:147], v[176:179], v[60:63]
	s_waitcnt lgkmcnt(3)
	v_mfma_f32_16x16x32_f16 v[64:67], v[148:151], v[164:167], v[64:67]
	v_mfma_f32_16x16x32_f16 v[68:71], v[148:151], v[168:171], v[68:71]
	v_mfma_f32_16x16x32_f16 v[72:75], v[148:151], v[172:175], v[72:75]
	v_mfma_f32_16x16x32_f16 v[76:79], v[148:151], v[176:179], v[76:79]
	s_waitcnt lgkmcnt(2)
	v_mfma_f32_16x16x32_f16 v[80:83], v[152:155], v[164:167], v[80:83]
	v_mfma_f32_16x16x32_f16 v[84:87], v[152:155], v[168:171], v[84:87]
	v_mfma_f32_16x16x32_f16 v[88:91], v[152:155], v[172:175], v[88:91]
	v_mfma_f32_16x16x32_f16 v[92:95], v[152:155], v[176:179], v[92:95]
	s_waitcnt lgkmcnt(1)
	v_mfma_f32_16x16x32_f16 v[96:99], v[156:159], v[164:167], v[96:99]
	v_mfma_f32_16x16x32_f16 v[100:103], v[156:159], v[168:171], v[100:103]
	v_mfma_f32_16x16x32_f16 v[104:107], v[156:159], v[172:175], v[104:107]
	v_mfma_f32_16x16x32_f16 v[108:111], v[156:159], v[176:179], v[108:111]
	s_waitcnt lgkmcnt(0)
	v_mfma_f32_16x16x32_f16 v[116:119], v[160:163], v[164:167], v[116:119]
	v_mfma_f32_16x16x32_f16 v[120:123], v[160:163], v[168:171], v[120:123]
	v_mfma_f32_16x16x32_f16 v[124:127], v[160:163], v[172:175], v[124:127]
	v_mfma_f32_16x16x32_f16 v[128:131], v[160:163], v[176:179], v[128:131]
	s_sub_u32 s16, s16, 1
	s_cmp_lg_u32 s16, 0
	s_cbranch_scc1 .Lg3_sw1
	s_nop 7
	s_mov_b64 s[100:101], s[98:99]
	v_mul_f32_e32 v238, 0xbfb8aa3b, v0
	v_exp_f32_e32 v238, v238
	s_nop 0
	v_add_f32_e32 v239, 1.0, v238
	v_div_scale_f32 v240, s[8:9], v239, v239, v0
	v_rcp_f32_e32 v241, v240
	v_div_scale_f32 v242, vcc, v0, v239, v0
	v_fma_f32 v243, -v240, v241, 1.0
	v_fmac_f32_e32 v241, v243, v241
	v_mul_f32_e32 v244, v242, v241
	v_fma_f32 v243, -v240, v244, v242
	v_fmac_f32_e32 v244, v243, v241
	v_fma_f32 v240, -v240, v244, v242
	v_div_fmas_f32 v240, v240, v241, v244
	v_div_fixup_f32 v240, v240, v239, v0
	v_mul_f32_e32 v240, v8, v240
	v_med3_f32 v240, v240, s57, v194
	v_cvt_f16_f32_e32 v245, v240
	v_mul_f32_e32 v238, 0xbfb8aa3b, v4
	v_exp_f32_e32 v238, v238
	s_nop 0
	v_add_f32_e32 v239, 1.0, v238
	v_div_scale_f32 v240, s[8:9], v239, v239, v4
	v_rcp_f32_e32 v241, v240
	v_div_scale_f32 v242, vcc, v4, v239, v4
	v_fma_f32 v243, -v240, v241, 1.0
	v_fmac_f32_e32 v241, v243, v241
	v_mul_f32_e32 v244, v242, v241
	v_fma_f32 v243, -v240, v244, v242
	v_fmac_f32_e32 v244, v243, v241
	v_fma_f32 v240, -v240, v244, v242
	v_div_fmas_f32 v240, v240, v241, v244
	v_div_fixup_f32 v240, v240, v239, v4
	v_mul_f32_e32 v240, v12, v240
	v_med3_f32 v240, v240, s57, v194
	v_cvt_f16_f32_e32 v246, v240
	global_store_short v237, v245, s[100:101]
	global_store_short v237, v246, s[100:101] offset:32
	s_add_u32 s100, s98, 0x1600
	s_addc_u32 s101, s99, 0
	v_mul_f32_e32 v238, 0xbfb8aa3b, v1
	v_exp_f32_e32 v238, v238
	s_nop 0
	v_add_f32_e32 v239, 1.0, v238
	v_div_scale_f32 v240, s[8:9], v239, v239, v1
	v_rcp_f32_e32 v241, v240
	v_div_scale_f32 v242, vcc, v1, v239, v1
	v_fma_f32 v243, -v240, v241, 1.0
	v_fmac_f32_e32 v241, v243, v241
	v_mul_f32_e32 v244, v242, v241
	v_fma_f32 v243, -v240, v244, v242
	v_fmac_f32_e32 v244, v243, v241
	v_fma_f32 v240, -v240, v244, v242
	v_div_fmas_f32 v240, v240, v241, v244
	v_div_fixup_f32 v240, v240, v239, v1
	v_mul_f32_e32 v240, v9, v240
	v_med3_f32 v240, v240, s57, v194
	v_cvt_f16_f32_e32 v245, v240
	v_mul_f32_e32 v238, 0xbfb8aa3b, v5
	v_exp_f32_e32 v238, v238
	s_nop 0
	v_add_f32_e32 v239, 1.0, v238
	v_div_scale_f32 v240, s[8:9], v239, v239, v5
	v_rcp_f32_e32 v241, v240
	v_div_scale_f32 v242, vcc, v5, v239, v5
	v_fma_f32 v243, -v240, v241, 1.0
	v_fmac_f32_e32 v241, v243, v241
	v_mul_f32_e32 v244, v242, v241
	v_fma_f32 v243, -v240, v244, v242
	v_fmac_f32_e32 v244, v243, v241
	v_fma_f32 v240, -v240, v244, v242
	v_div_fmas_f32 v240, v240, v241, v244
	v_div_fixup_f32 v240, v240, v239, v5
	v_mul_f32_e32 v240, v13, v240
	v_med3_f32 v240, v240, s57, v194
	v_cvt_f16_f32_e32 v246, v240
	global_store_short v237, v245, s[100:101]
	global_store_short v237, v246, s[100:101] offset:32
	s_add_u32 s100, s98, 0x2c00
	s_addc_u32 s101, s99, 0
	v_mul_f32_e32 v238, 0xbfb8aa3b, v2
	v_exp_f32_e32 v238, v238
	s_nop 0
	v_add_f32_e32 v239, 1.0, v238
	v_div_scale_f32 v240, s[8:9], v239, v239, v2
	v_rcp_f32_e32 v241, v240
	v_div_scale_f32 v242, vcc, v2, v239, v2
	v_fma_f32 v243, -v240, v241, 1.0
	v_fmac_f32_e32 v241, v243, v241
	v_mul_f32_e32 v244, v242, v241
	v_fma_f32 v243, -v240, v244, v242
	v_fmac_f32_e32 v244, v243, v241
	v_fma_f32 v240, -v240, v244, v242
	v_div_fmas_f32 v240, v240, v241, v244
	v_div_fixup_f32 v240, v240, v239, v2
	v_mul_f32_e32 v240, v10, v240
	v_med3_f32 v240, v240, s57, v194
	v_cvt_f16_f32_e32 v245, v240
	v_mul_f32_e32 v238, 0xbfb8aa3b, v6
	v_exp_f32_e32 v238, v238
	s_nop 0
	v_add_f32_e32 v239, 1.0, v238
	v_div_scale_f32 v240, s[8:9], v239, v239, v6
	v_rcp_f32_e32 v241, v240
	v_div_scale_f32 v242, vcc, v6, v239, v6
	v_fma_f32 v243, -v240, v241, 1.0
	v_fmac_f32_e32 v241, v243, v241
	v_mul_f32_e32 v244, v242, v241
	v_fma_f32 v243, -v240, v244, v242
	v_fmac_f32_e32 v244, v243, v241
	v_fma_f32 v240, -v240, v244, v242
	v_div_fmas_f32 v240, v240, v241, v244
	v_div_fixup_f32 v240, v240, v239, v6
	v_mul_f32_e32 v240, v14, v240
	v_med3_f32 v240, v240, s57, v194
	v_cvt_f16_f32_e32 v246, v240
	global_store_short v237, v245, s[100:101]
	global_store_short v237, v246, s[100:101] offset:32
	s_add_u32 s100, s98, 0x4200
	s_addc_u32 s101, s99, 0
	v_mul_f32_e32 v238, 0xbfb8aa3b, v3
	v_exp_f32_e32 v238, v238
	s_nop 0
	v_add_f32_e32 v239, 1.0, v238
	v_div_scale_f32 v240, s[8:9], v239, v239, v3
	v_rcp_f32_e32 v241, v240
	v_div_scale_f32 v242, vcc, v3, v239, v3
	v_fma_f32 v243, -v240, v241, 1.0
	v_fmac_f32_e32 v241, v243, v241
	v_mul_f32_e32 v244, v242, v241
	v_fma_f32 v243, -v240, v244, v242
	v_fmac_f32_e32 v244, v243, v241
	v_fma_f32 v240, -v240, v244, v242
	v_div_fmas_f32 v240, v240, v241, v244
	v_div_fixup_f32 v240, v240, v239, v3
	v_mul_f32_e32 v240, v11, v240
	v_med3_f32 v240, v240, s57, v194
	v_cvt_f16_f32_e32 v245, v240
	v_mul_f32_e32 v238, 0xbfb8aa3b, v7
	v_exp_f32_e32 v238, v238
	s_nop 0
	v_add_f32_e32 v239, 1.0, v238
	v_div_scale_f32 v240, s[8:9], v239, v239, v7
	v_rcp_f32_e32 v241, v240
	v_div_scale_f32 v242, vcc, v7, v239, v7
	v_fma_f32 v243, -v240, v241, 1.0
	v_fmac_f32_e32 v241, v243, v241
	v_mul_f32_e32 v244, v242, v241
	v_fma_f32 v243, -v240, v244, v242
	v_fmac_f32_e32 v244, v243, v241
	v_fma_f32 v240, -v240, v244, v242
	v_div_fmas_f32 v240, v240, v241, v244
	v_div_fixup_f32 v240, v240, v239, v7
	v_mul_f32_e32 v240, v15, v240
	v_med3_f32 v240, v240, s57, v194
	v_cvt_f16_f32_e32 v246, v240
	global_store_short v237, v245, s[100:101]
	global_store_short v237, v246, s[100:101] offset:32
	s_add_u32 s100, s98, 0x16000
	s_addc_u32 s101, s99, 0
	v_mul_f32_e32 v238, 0xbfb8aa3b, v16
	v_exp_f32_e32 v238, v238
	s_nop 0
	v_add_f32_e32 v239, 1.0, v238
	v_div_scale_f32 v240, s[8:9], v239, v239, v16
	v_rcp_f32_e32 v241, v240
	v_div_scale_f32 v242, vcc, v16, v239, v16
	v_fma_f32 v243, -v240, v241, 1.0
	v_fmac_f32_e32 v241, v243, v241
	v_mul_f32_e32 v244, v242, v241
	v_fma_f32 v243, -v240, v244, v242
	v_fmac_f32_e32 v244, v243, v241
	v_fma_f32 v240, -v240, v244, v242
	v_div_fmas_f32 v240, v240, v241, v244
	v_div_fixup_f32 v240, v240, v239, v16
	v_mul_f32_e32 v240, v24, v240
	v_med3_f32 v240, v240, s57, v194
	v_cvt_f16_f32_e32 v245, v240
	v_mul_f32_e32 v238, 0xbfb8aa3b, v20
	v_exp_f32_e32 v238, v238
	s_nop 0
	v_add_f32_e32 v239, 1.0, v238
	v_div_scale_f32 v240, s[8:9], v239, v239, v20
	v_rcp_f32_e32 v241, v240
	v_div_scale_f32 v242, vcc, v20, v239, v20
	v_fma_f32 v243, -v240, v241, 1.0
	v_fmac_f32_e32 v241, v243, v241
	v_mul_f32_e32 v244, v242, v241
	v_fma_f32 v243, -v240, v244, v242
	v_fmac_f32_e32 v244, v243, v241
	v_fma_f32 v240, -v240, v244, v242
	v_div_fmas_f32 v240, v240, v241, v244
	v_div_fixup_f32 v240, v240, v239, v20
	v_mul_f32_e32 v240, v28, v240
	v_med3_f32 v240, v240, s57, v194
	v_cvt_f16_f32_e32 v246, v240
	global_store_short v237, v245, s[100:101]
	global_store_short v237, v246, s[100:101] offset:32
	s_add_u32 s100, s98, 0x17600
	s_addc_u32 s101, s99, 0
	v_mul_f32_e32 v238, 0xbfb8aa3b, v17
	v_exp_f32_e32 v238, v238
	s_nop 0
	v_add_f32_e32 v239, 1.0, v238
	v_div_scale_f32 v240, s[8:9], v239, v239, v17
	v_rcp_f32_e32 v241, v240
	v_div_scale_f32 v242, vcc, v17, v239, v17
	v_fma_f32 v243, -v240, v241, 1.0
	v_fmac_f32_e32 v241, v243, v241
	v_mul_f32_e32 v244, v242, v241
	v_fma_f32 v243, -v240, v244, v242
	v_fmac_f32_e32 v244, v243, v241
	v_fma_f32 v240, -v240, v244, v242
	v_div_fmas_f32 v240, v240, v241, v244
	v_div_fixup_f32 v240, v240, v239, v17
	v_mul_f32_e32 v240, v25, v240
	v_med3_f32 v240, v240, s57, v194
	v_cvt_f16_f32_e32 v245, v240
	v_mul_f32_e32 v238, 0xbfb8aa3b, v21
	v_exp_f32_e32 v238, v238
	s_nop 0
	v_add_f32_e32 v239, 1.0, v238
	v_div_scale_f32 v240, s[8:9], v239, v239, v21
	v_rcp_f32_e32 v241, v240
	v_div_scale_f32 v242, vcc, v21, v239, v21
	v_fma_f32 v243, -v240, v241, 1.0
	v_fmac_f32_e32 v241, v243, v241
	v_mul_f32_e32 v244, v242, v241
	v_fma_f32 v243, -v240, v244, v242
	v_fmac_f32_e32 v244, v243, v241
	v_fma_f32 v240, -v240, v244, v242
	v_div_fmas_f32 v240, v240, v241, v244
	v_div_fixup_f32 v240, v240, v239, v21
	v_mul_f32_e32 v240, v29, v240
	v_med3_f32 v240, v240, s57, v194
	v_cvt_f16_f32_e32 v246, v240
	global_store_short v237, v245, s[100:101]
	global_store_short v237, v246, s[100:101] offset:32
	s_add_u32 s100, s98, 0x18c00
	s_addc_u32 s101, s99, 0
	v_mul_f32_e32 v238, 0xbfb8aa3b, v18
	v_exp_f32_e32 v238, v238
	s_nop 0
	v_add_f32_e32 v239, 1.0, v238
	v_div_scale_f32 v240, s[8:9], v239, v239, v18
	v_rcp_f32_e32 v241, v240
	v_div_scale_f32 v242, vcc, v18, v239, v18
	v_fma_f32 v243, -v240, v241, 1.0
	v_fmac_f32_e32 v241, v243, v241
	v_mul_f32_e32 v244, v242, v241
	v_fma_f32 v243, -v240, v244, v242
	v_fmac_f32_e32 v244, v243, v241
	v_fma_f32 v240, -v240, v244, v242
	v_div_fmas_f32 v240, v240, v241, v244
	v_div_fixup_f32 v240, v240, v239, v18
	v_mul_f32_e32 v240, v26, v240
	v_med3_f32 v240, v240, s57, v194
	v_cvt_f16_f32_e32 v245, v240
	v_mul_f32_e32 v238, 0xbfb8aa3b, v22
	v_exp_f32_e32 v238, v238
	s_nop 0
	v_add_f32_e32 v239, 1.0, v238
	v_div_scale_f32 v240, s[8:9], v239, v239, v22
	v_rcp_f32_e32 v241, v240
	v_div_scale_f32 v242, vcc, v22, v239, v22
	v_fma_f32 v243, -v240, v241, 1.0
	v_fmac_f32_e32 v241, v243, v241
	v_mul_f32_e32 v244, v242, v241
	v_fma_f32 v243, -v240, v244, v242
	v_fmac_f32_e32 v244, v243, v241
	v_fma_f32 v240, -v240, v244, v242
	v_div_fmas_f32 v240, v240, v241, v244
	v_div_fixup_f32 v240, v240, v239, v22
	v_mul_f32_e32 v240, v30, v240
	v_med3_f32 v240, v240, s57, v194
	v_cvt_f16_f32_e32 v246, v240
	global_store_short v237, v245, s[100:101]
	global_store_short v237, v246, s[100:101] offset:32
	s_add_u32 s100, s98, 0x1a200
	s_addc_u32 s101, s99, 0
	v_mul_f32_e32 v238, 0xbfb8aa3b, v19
	v_exp_f32_e32 v238, v238
	s_nop 0
	v_add_f32_e32 v239, 1.0, v238
	v_div_scale_f32 v240, s[8:9], v239, v239, v19
	v_rcp_f32_e32 v241, v240
	v_div_scale_f32 v242, vcc, v19, v239, v19
	v_fma_f32 v243, -v240, v241, 1.0
	v_fmac_f32_e32 v241, v243, v241
	v_mul_f32_e32 v244, v242, v241
	v_fma_f32 v243, -v240, v244, v242
	v_fmac_f32_e32 v244, v243, v241
	v_fma_f32 v240, -v240, v244, v242
	v_div_fmas_f32 v240, v240, v241, v244
	v_div_fixup_f32 v240, v240, v239, v19
	v_mul_f32_e32 v240, v27, v240
	v_med3_f32 v240, v240, s57, v194
	v_cvt_f16_f32_e32 v245, v240
	v_mul_f32_e32 v238, 0xbfb8aa3b, v23
	v_exp_f32_e32 v238, v238
	s_nop 0
	v_add_f32_e32 v239, 1.0, v238
	v_div_scale_f32 v240, s[8:9], v239, v239, v23
	v_rcp_f32_e32 v241, v240
	v_div_scale_f32 v242, vcc, v23, v239, v23
	v_fma_f32 v243, -v240, v241, 1.0
	v_fmac_f32_e32 v241, v243, v241
	v_mul_f32_e32 v244, v242, v241
	v_fma_f32 v243, -v240, v244, v242
	v_fmac_f32_e32 v244, v243, v241
	v_fma_f32 v240, -v240, v244, v242
	v_div_fmas_f32 v240, v240, v241, v244
	v_div_fixup_f32 v240, v240, v239, v23
	v_mul_f32_e32 v240, v31, v240
	v_med3_f32 v240, v240, s57, v194
	v_cvt_f16_f32_e32 v246, v240
	global_store_short v237, v245, s[100:101]
	global_store_short v237, v246, s[100:101] offset:32
	s_add_u32 s100, s98, 0x2c000
	s_addc_u32 s101, s99, 0
	v_mul_f32_e32 v238, 0xbfb8aa3b, v32
	v_exp_f32_e32 v238, v238
	s_nop 0
	v_add_f32_e32 v239, 1.0, v238
	v_div_scale_f32 v240, s[8:9], v239, v239, v32
	v_rcp_f32_e32 v241, v240
	v_div_scale_f32 v242, vcc, v32, v239, v32
	v_fma_f32 v243, -v240, v241, 1.0
	v_fmac_f32_e32 v241, v243, v241
	v_mul_f32_e32 v244, v242, v241
	v_fma_f32 v243, -v240, v244, v242
	v_fmac_f32_e32 v244, v243, v241
	v_fma_f32 v240, -v240, v244, v242
	v_div_fmas_f32 v240, v240, v241, v244
	v_div_fixup_f32 v240, v240, v239, v32
	v_mul_f32_e32 v240, v40, v240
	v_med3_f32 v240, v240, s57, v194
	v_cvt_f16_f32_e32 v245, v240
	v_mul_f32_e32 v238, 0xbfb8aa3b, v36
	v_exp_f32_e32 v238, v238
	s_nop 0
	v_add_f32_e32 v239, 1.0, v238
	v_div_scale_f32 v240, s[8:9], v239, v239, v36
	v_rcp_f32_e32 v241, v240
	v_div_scale_f32 v242, vcc, v36, v239, v36
	v_fma_f32 v243, -v240, v241, 1.0
	v_fmac_f32_e32 v241, v243, v241
	v_mul_f32_e32 v244, v242, v241
	v_fma_f32 v243, -v240, v244, v242
	v_fmac_f32_e32 v244, v243, v241
	v_fma_f32 v240, -v240, v244, v242
	v_div_fmas_f32 v240, v240, v241, v244
	v_div_fixup_f32 v240, v240, v239, v36
	v_mul_f32_e32 v240, v44, v240
	v_med3_f32 v240, v240, s57, v194
	v_cvt_f16_f32_e32 v246, v240
	global_store_short v237, v245, s[100:101]
	global_store_short v237, v246, s[100:101] offset:32
	s_add_u32 s100, s98, 0x2d600
	s_addc_u32 s101, s99, 0
	v_mul_f32_e32 v238, 0xbfb8aa3b, v33
	v_exp_f32_e32 v238, v238
	s_nop 0
	v_add_f32_e32 v239, 1.0, v238
	v_div_scale_f32 v240, s[8:9], v239, v239, v33
	v_rcp_f32_e32 v241, v240
	v_div_scale_f32 v242, vcc, v33, v239, v33
	v_fma_f32 v243, -v240, v241, 1.0
	v_fmac_f32_e32 v241, v243, v241
	v_mul_f32_e32 v244, v242, v241
	v_fma_f32 v243, -v240, v244, v242
	v_fmac_f32_e32 v244, v243, v241
	v_fma_f32 v240, -v240, v244, v242
	v_div_fmas_f32 v240, v240, v241, v244
	v_div_fixup_f32 v240, v240, v239, v33
	v_mul_f32_e32 v240, v41, v240
	v_med3_f32 v240, v240, s57, v194
	v_cvt_f16_f32_e32 v245, v240
	v_mul_f32_e32 v238, 0xbfb8aa3b, v37
	v_exp_f32_e32 v238, v238
	s_nop 0
	v_add_f32_e32 v239, 1.0, v238
	v_div_scale_f32 v240, s[8:9], v239, v239, v37
	v_rcp_f32_e32 v241, v240
	v_div_scale_f32 v242, vcc, v37, v239, v37
	v_fma_f32 v243, -v240, v241, 1.0
	v_fmac_f32_e32 v241, v243, v241
	v_mul_f32_e32 v244, v242, v241
	v_fma_f32 v243, -v240, v244, v242
	v_fmac_f32_e32 v244, v243, v241
	v_fma_f32 v240, -v240, v244, v242
	v_div_fmas_f32 v240, v240, v241, v244
	v_div_fixup_f32 v240, v240, v239, v37
	v_mul_f32_e32 v240, v45, v240
	v_med3_f32 v240, v240, s57, v194
	v_cvt_f16_f32_e32 v246, v240
	global_store_short v237, v245, s[100:101]
	global_store_short v237, v246, s[100:101] offset:32
	s_add_u32 s100, s98, 0x2ec00
	s_addc_u32 s101, s99, 0
	v_mul_f32_e32 v238, 0xbfb8aa3b, v34
	v_exp_f32_e32 v238, v238
	s_nop 0
	v_add_f32_e32 v239, 1.0, v238
	v_div_scale_f32 v240, s[8:9], v239, v239, v34
	v_rcp_f32_e32 v241, v240
	v_div_scale_f32 v242, vcc, v34, v239, v34
	v_fma_f32 v243, -v240, v241, 1.0
	v_fmac_f32_e32 v241, v243, v241
	v_mul_f32_e32 v244, v242, v241
	v_fma_f32 v243, -v240, v244, v242
	v_fmac_f32_e32 v244, v243, v241
	v_fma_f32 v240, -v240, v244, v242
	v_div_fmas_f32 v240, v240, v241, v244
	v_div_fixup_f32 v240, v240, v239, v34
	v_mul_f32_e32 v240, v42, v240
	v_med3_f32 v240, v240, s57, v194
	v_cvt_f16_f32_e32 v245, v240
	v_mul_f32_e32 v238, 0xbfb8aa3b, v38
	v_exp_f32_e32 v238, v238
	s_nop 0
	v_add_f32_e32 v239, 1.0, v238
	v_div_scale_f32 v240, s[8:9], v239, v239, v38
	v_rcp_f32_e32 v241, v240
	v_div_scale_f32 v242, vcc, v38, v239, v38
	v_fma_f32 v243, -v240, v241, 1.0
	v_fmac_f32_e32 v241, v243, v241
	v_mul_f32_e32 v244, v242, v241
	v_fma_f32 v243, -v240, v244, v242
	v_fmac_f32_e32 v244, v243, v241
	v_fma_f32 v240, -v240, v244, v242
	v_div_fmas_f32 v240, v240, v241, v244
	v_div_fixup_f32 v240, v240, v239, v38
	v_mul_f32_e32 v240, v46, v240
	v_med3_f32 v240, v240, s57, v194
	v_cvt_f16_f32_e32 v246, v240
	global_store_short v237, v245, s[100:101]
	global_store_short v237, v246, s[100:101] offset:32
	s_add_u32 s100, s98, 0x30200
	s_addc_u32 s101, s99, 0
	v_mul_f32_e32 v238, 0xbfb8aa3b, v35
	v_exp_f32_e32 v238, v238
	s_nop 0
	v_add_f32_e32 v239, 1.0, v238
	v_div_scale_f32 v240, s[8:9], v239, v239, v35
	v_rcp_f32_e32 v241, v240
	v_div_scale_f32 v242, vcc, v35, v239, v35
	v_fma_f32 v243, -v240, v241, 1.0
	v_fmac_f32_e32 v241, v243, v241
	v_mul_f32_e32 v244, v242, v241
	v_fma_f32 v243, -v240, v244, v242
	v_fmac_f32_e32 v244, v243, v241
	v_fma_f32 v240, -v240, v244, v242
	v_div_fmas_f32 v240, v240, v241, v244
	v_div_fixup_f32 v240, v240, v239, v35
	v_mul_f32_e32 v240, v43, v240
	v_med3_f32 v240, v240, s57, v194
	v_cvt_f16_f32_e32 v245, v240
	v_mul_f32_e32 v238, 0xbfb8aa3b, v39
	v_exp_f32_e32 v238, v238
	s_nop 0
	v_add_f32_e32 v239, 1.0, v238
	v_div_scale_f32 v240, s[8:9], v239, v239, v39
	v_rcp_f32_e32 v241, v240
	v_div_scale_f32 v242, vcc, v39, v239, v39
	v_fma_f32 v243, -v240, v241, 1.0
	v_fmac_f32_e32 v241, v243, v241
	v_mul_f32_e32 v244, v242, v241
	v_fma_f32 v243, -v240, v244, v242
	v_fmac_f32_e32 v244, v243, v241
	v_fma_f32 v240, -v240, v244, v242
	v_div_fmas_f32 v240, v240, v241, v244
	v_div_fixup_f32 v240, v240, v239, v39
	v_mul_f32_e32 v240, v47, v240
	v_med3_f32 v240, v240, s57, v194
	v_cvt_f16_f32_e32 v246, v240
	global_store_short v237, v245, s[100:101]
	global_store_short v237, v246, s[100:101] offset:32
	s_add_u32 s100, s98, 0x42000
	s_addc_u32 s101, s99, 0
	v_mul_f32_e32 v238, 0xbfb8aa3b, v48
	v_exp_f32_e32 v238, v238
	s_nop 0
	v_add_f32_e32 v239, 1.0, v238
	v_div_scale_f32 v240, s[8:9], v239, v239, v48
	v_rcp_f32_e32 v241, v240
	v_div_scale_f32 v242, vcc, v48, v239, v48
	v_fma_f32 v243, -v240, v241, 1.0
	v_fmac_f32_e32 v241, v243, v241
	v_mul_f32_e32 v244, v242, v241
	v_fma_f32 v243, -v240, v244, v242
	v_fmac_f32_e32 v244, v243, v241
	v_fma_f32 v240, -v240, v244, v242
	v_div_fmas_f32 v240, v240, v241, v244
	v_div_fixup_f32 v240, v240, v239, v48
	v_mul_f32_e32 v240, v56, v240
	v_med3_f32 v240, v240, s57, v194
	v_cvt_f16_f32_e32 v245, v240
	v_mul_f32_e32 v238, 0xbfb8aa3b, v52
	v_exp_f32_e32 v238, v238
	s_nop 0
	v_add_f32_e32 v239, 1.0, v238
	v_div_scale_f32 v240, s[8:9], v239, v239, v52
	v_rcp_f32_e32 v241, v240
	v_div_scale_f32 v242, vcc, v52, v239, v52
	v_fma_f32 v243, -v240, v241, 1.0
	v_fmac_f32_e32 v241, v243, v241
	v_mul_f32_e32 v244, v242, v241
	v_fma_f32 v243, -v240, v244, v242
	v_fmac_f32_e32 v244, v243, v241
	v_fma_f32 v240, -v240, v244, v242
	v_div_fmas_f32 v240, v240, v241, v244
	v_div_fixup_f32 v240, v240, v239, v52
	v_mul_f32_e32 v240, v60, v240
	v_med3_f32 v240, v240, s57, v194
	v_cvt_f16_f32_e32 v246, v240
	global_store_short v237, v245, s[100:101]
	global_store_short v237, v246, s[100:101] offset:32
	s_add_u32 s100, s98, 0x43600
	s_addc_u32 s101, s99, 0
	v_mul_f32_e32 v238, 0xbfb8aa3b, v49
	v_exp_f32_e32 v238, v238
	s_nop 0
	v_add_f32_e32 v239, 1.0, v238
	v_div_scale_f32 v240, s[8:9], v239, v239, v49
	v_rcp_f32_e32 v241, v240
	v_div_scale_f32 v242, vcc, v49, v239, v49
	v_fma_f32 v243, -v240, v241, 1.0
	v_fmac_f32_e32 v241, v243, v241
	v_mul_f32_e32 v244, v242, v241
	v_fma_f32 v243, -v240, v244, v242
	v_fmac_f32_e32 v244, v243, v241
	v_fma_f32 v240, -v240, v244, v242
	v_div_fmas_f32 v240, v240, v241, v244
	v_div_fixup_f32 v240, v240, v239, v49
	v_mul_f32_e32 v240, v57, v240
	v_med3_f32 v240, v240, s57, v194
	v_cvt_f16_f32_e32 v245, v240
	v_mul_f32_e32 v238, 0xbfb8aa3b, v53
	v_exp_f32_e32 v238, v238
	s_nop 0
	v_add_f32_e32 v239, 1.0, v238
	v_div_scale_f32 v240, s[8:9], v239, v239, v53
	v_rcp_f32_e32 v241, v240
	v_div_scale_f32 v242, vcc, v53, v239, v53
	v_fma_f32 v243, -v240, v241, 1.0
	v_fmac_f32_e32 v241, v243, v241
	v_mul_f32_e32 v244, v242, v241
	v_fma_f32 v243, -v240, v244, v242
	v_fmac_f32_e32 v244, v243, v241
	v_fma_f32 v240, -v240, v244, v242
	v_div_fmas_f32 v240, v240, v241, v244
	v_div_fixup_f32 v240, v240, v239, v53
	v_mul_f32_e32 v240, v61, v240
	v_med3_f32 v240, v240, s57, v194
	v_cvt_f16_f32_e32 v246, v240
	global_store_short v237, v245, s[100:101]
	global_store_short v237, v246, s[100:101] offset:32
	s_add_u32 s100, s98, 0x44c00
	s_addc_u32 s101, s99, 0
	v_mul_f32_e32 v238, 0xbfb8aa3b, v50
	v_exp_f32_e32 v238, v238
	s_nop 0
	v_add_f32_e32 v239, 1.0, v238
	v_div_scale_f32 v240, s[8:9], v239, v239, v50
	v_rcp_f32_e32 v241, v240
	v_div_scale_f32 v242, vcc, v50, v239, v50
	v_fma_f32 v243, -v240, v241, 1.0
	v_fmac_f32_e32 v241, v243, v241
	v_mul_f32_e32 v244, v242, v241
	v_fma_f32 v243, -v240, v244, v242
	v_fmac_f32_e32 v244, v243, v241
	v_fma_f32 v240, -v240, v244, v242
	v_div_fmas_f32 v240, v240, v241, v244
	v_div_fixup_f32 v240, v240, v239, v50
	v_mul_f32_e32 v240, v58, v240
	v_med3_f32 v240, v240, s57, v194
	v_cvt_f16_f32_e32 v245, v240
	v_mul_f32_e32 v238, 0xbfb8aa3b, v54
	v_exp_f32_e32 v238, v238
	s_nop 0
	v_add_f32_e32 v239, 1.0, v238
	v_div_scale_f32 v240, s[8:9], v239, v239, v54
	v_rcp_f32_e32 v241, v240
	v_div_scale_f32 v242, vcc, v54, v239, v54
	v_fma_f32 v243, -v240, v241, 1.0
	v_fmac_f32_e32 v241, v243, v241
	v_mul_f32_e32 v244, v242, v241
	v_fma_f32 v243, -v240, v244, v242
	v_fmac_f32_e32 v244, v243, v241
	v_fma_f32 v240, -v240, v244, v242
	v_div_fmas_f32 v240, v240, v241, v244
	v_div_fixup_f32 v240, v240, v239, v54
	v_mul_f32_e32 v240, v62, v240
	v_med3_f32 v240, v240, s57, v194
	v_cvt_f16_f32_e32 v246, v240
	global_store_short v237, v245, s[100:101]
	global_store_short v237, v246, s[100:101] offset:32
	s_add_u32 s100, s98, 0x46200
	s_addc_u32 s101, s99, 0
	v_mul_f32_e32 v238, 0xbfb8aa3b, v51
	v_exp_f32_e32 v238, v238
	s_nop 0
	v_add_f32_e32 v239, 1.0, v238
	v_div_scale_f32 v240, s[8:9], v239, v239, v51
	v_rcp_f32_e32 v241, v240
	v_div_scale_f32 v242, vcc, v51, v239, v51
	v_fma_f32 v243, -v240, v241, 1.0
	v_fmac_f32_e32 v241, v243, v241
	v_mul_f32_e32 v244, v242, v241
	v_fma_f32 v243, -v240, v244, v242
	v_fmac_f32_e32 v244, v243, v241
	v_fma_f32 v240, -v240, v244, v242
	v_div_fmas_f32 v240, v240, v241, v244
	v_div_fixup_f32 v240, v240, v239, v51
	v_mul_f32_e32 v240, v59, v240
	v_med3_f32 v240, v240, s57, v194
	v_cvt_f16_f32_e32 v245, v240
	v_mul_f32_e32 v238, 0xbfb8aa3b, v55
	v_exp_f32_e32 v238, v238
	s_nop 0
	v_add_f32_e32 v239, 1.0, v238
	v_div_scale_f32 v240, s[8:9], v239, v239, v55
	v_rcp_f32_e32 v241, v240
	v_div_scale_f32 v242, vcc, v55, v239, v55
	v_fma_f32 v243, -v240, v241, 1.0
	v_fmac_f32_e32 v241, v243, v241
	v_mul_f32_e32 v244, v242, v241
	v_fma_f32 v243, -v240, v244, v242
	v_fmac_f32_e32 v244, v243, v241
	v_fma_f32 v240, -v240, v244, v242
	v_div_fmas_f32 v240, v240, v241, v244
	v_div_fixup_f32 v240, v240, v239, v55
	v_mul_f32_e32 v240, v63, v240
	v_med3_f32 v240, v240, s57, v194
	v_cvt_f16_f32_e32 v246, v240
	global_store_short v237, v245, s[100:101]
	global_store_short v237, v246, s[100:101] offset:32
	s_add_u32 s100, s98, 0x58000
	s_addc_u32 s101, s99, 0
	v_mul_f32_e32 v238, 0xbfb8aa3b, v64
	v_exp_f32_e32 v238, v238
	s_nop 0
	v_add_f32_e32 v239, 1.0, v238
	v_div_scale_f32 v240, s[8:9], v239, v239, v64
	v_rcp_f32_e32 v241, v240
	v_div_scale_f32 v242, vcc, v64, v239, v64
	v_fma_f32 v243, -v240, v241, 1.0
	v_fmac_f32_e32 v241, v243, v241
	v_mul_f32_e32 v244, v242, v241
	v_fma_f32 v243, -v240, v244, v242
	v_fmac_f32_e32 v244, v243, v241
	v_fma_f32 v240, -v240, v244, v242
	v_div_fmas_f32 v240, v240, v241, v244
	v_div_fixup_f32 v240, v240, v239, v64
	v_mul_f32_e32 v240, v72, v240
	v_med3_f32 v240, v240, s57, v194
	v_cvt_f16_f32_e32 v245, v240
	v_mul_f32_e32 v238, 0xbfb8aa3b, v68
	v_exp_f32_e32 v238, v238
	s_nop 0
	v_add_f32_e32 v239, 1.0, v238
	v_div_scale_f32 v240, s[8:9], v239, v239, v68
	v_rcp_f32_e32 v241, v240
	v_div_scale_f32 v242, vcc, v68, v239, v68
	v_fma_f32 v243, -v240, v241, 1.0
	v_fmac_f32_e32 v241, v243, v241
	v_mul_f32_e32 v244, v242, v241
	v_fma_f32 v243, -v240, v244, v242
	v_fmac_f32_e32 v244, v243, v241
	v_fma_f32 v240, -v240, v244, v242
	v_div_fmas_f32 v240, v240, v241, v244
	v_div_fixup_f32 v240, v240, v239, v68
	v_mul_f32_e32 v240, v76, v240
	v_med3_f32 v240, v240, s57, v194
	v_cvt_f16_f32_e32 v246, v240
	global_store_short v237, v245, s[100:101]
	global_store_short v237, v246, s[100:101] offset:32
	s_add_u32 s100, s98, 0x59600
	s_addc_u32 s101, s99, 0
	v_mul_f32_e32 v238, 0xbfb8aa3b, v65
	v_exp_f32_e32 v238, v238
	s_nop 0
	v_add_f32_e32 v239, 1.0, v238
	v_div_scale_f32 v240, s[8:9], v239, v239, v65
	v_rcp_f32_e32 v241, v240
	v_div_scale_f32 v242, vcc, v65, v239, v65
	v_fma_f32 v243, -v240, v241, 1.0
	v_fmac_f32_e32 v241, v243, v241
	v_mul_f32_e32 v244, v242, v241
	v_fma_f32 v243, -v240, v244, v242
	v_fmac_f32_e32 v244, v243, v241
	v_fma_f32 v240, -v240, v244, v242
	v_div_fmas_f32 v240, v240, v241, v244
	v_div_fixup_f32 v240, v240, v239, v65
	v_mul_f32_e32 v240, v73, v240
	v_med3_f32 v240, v240, s57, v194
	v_cvt_f16_f32_e32 v245, v240
	v_mul_f32_e32 v238, 0xbfb8aa3b, v69
	v_exp_f32_e32 v238, v238
	s_nop 0
	v_add_f32_e32 v239, 1.0, v238
	v_div_scale_f32 v240, s[8:9], v239, v239, v69
	v_rcp_f32_e32 v241, v240
	v_div_scale_f32 v242, vcc, v69, v239, v69
	v_fma_f32 v243, -v240, v241, 1.0
	v_fmac_f32_e32 v241, v243, v241
	v_mul_f32_e32 v244, v242, v241
	v_fma_f32 v243, -v240, v244, v242
	v_fmac_f32_e32 v244, v243, v241
	v_fma_f32 v240, -v240, v244, v242
	v_div_fmas_f32 v240, v240, v241, v244
	v_div_fixup_f32 v240, v240, v239, v69
	v_mul_f32_e32 v240, v77, v240
	v_med3_f32 v240, v240, s57, v194
	v_cvt_f16_f32_e32 v246, v240
	global_store_short v237, v245, s[100:101]
	global_store_short v237, v246, s[100:101] offset:32
	s_add_u32 s100, s98, 0x5ac00
	s_addc_u32 s101, s99, 0
	v_mul_f32_e32 v238, 0xbfb8aa3b, v66
	v_exp_f32_e32 v238, v238
	s_nop 0
	v_add_f32_e32 v239, 1.0, v238
	v_div_scale_f32 v240, s[8:9], v239, v239, v66
	v_rcp_f32_e32 v241, v240
	v_div_scale_f32 v242, vcc, v66, v239, v66
	v_fma_f32 v243, -v240, v241, 1.0
	v_fmac_f32_e32 v241, v243, v241
	v_mul_f32_e32 v244, v242, v241
	v_fma_f32 v243, -v240, v244, v242
	v_fmac_f32_e32 v244, v243, v241
	v_fma_f32 v240, -v240, v244, v242
	v_div_fmas_f32 v240, v240, v241, v244
	v_div_fixup_f32 v240, v240, v239, v66
	v_mul_f32_e32 v240, v74, v240
	v_med3_f32 v240, v240, s57, v194
	v_cvt_f16_f32_e32 v245, v240
	v_mul_f32_e32 v238, 0xbfb8aa3b, v70
	v_exp_f32_e32 v238, v238
	s_nop 0
	v_add_f32_e32 v239, 1.0, v238
	v_div_scale_f32 v240, s[8:9], v239, v239, v70
	v_rcp_f32_e32 v241, v240
	v_div_scale_f32 v242, vcc, v70, v239, v70
	v_fma_f32 v243, -v240, v241, 1.0
	v_fmac_f32_e32 v241, v243, v241
	v_mul_f32_e32 v244, v242, v241
	v_fma_f32 v243, -v240, v244, v242
	v_fmac_f32_e32 v244, v243, v241
	v_fma_f32 v240, -v240, v244, v242
	v_div_fmas_f32 v240, v240, v241, v244
	v_div_fixup_f32 v240, v240, v239, v70
	v_mul_f32_e32 v240, v78, v240
	v_med3_f32 v240, v240, s57, v194
	v_cvt_f16_f32_e32 v246, v240
	global_store_short v237, v245, s[100:101]
	global_store_short v237, v246, s[100:101] offset:32
	s_add_u32 s100, s98, 0x5c200
	s_addc_u32 s101, s99, 0
	v_mul_f32_e32 v238, 0xbfb8aa3b, v67
	v_exp_f32_e32 v238, v238
	s_nop 0
	v_add_f32_e32 v239, 1.0, v238
	v_div_scale_f32 v240, s[8:9], v239, v239, v67
	v_rcp_f32_e32 v241, v240
	v_div_scale_f32 v242, vcc, v67, v239, v67
	v_fma_f32 v243, -v240, v241, 1.0
	v_fmac_f32_e32 v241, v243, v241
	v_mul_f32_e32 v244, v242, v241
	v_fma_f32 v243, -v240, v244, v242
	v_fmac_f32_e32 v244, v243, v241
	v_fma_f32 v240, -v240, v244, v242
	v_div_fmas_f32 v240, v240, v241, v244
	v_div_fixup_f32 v240, v240, v239, v67
	v_mul_f32_e32 v240, v75, v240
	v_med3_f32 v240, v240, s57, v194
	v_cvt_f16_f32_e32 v245, v240
	v_mul_f32_e32 v238, 0xbfb8aa3b, v71
	v_exp_f32_e32 v238, v238
	s_nop 0
	v_add_f32_e32 v239, 1.0, v238
	v_div_scale_f32 v240, s[8:9], v239, v239, v71
	v_rcp_f32_e32 v241, v240
	v_div_scale_f32 v242, vcc, v71, v239, v71
	v_fma_f32 v243, -v240, v241, 1.0
	v_fmac_f32_e32 v241, v243, v241
	v_mul_f32_e32 v244, v242, v241
	v_fma_f32 v243, -v240, v244, v242
	v_fmac_f32_e32 v244, v243, v241
	v_fma_f32 v240, -v240, v244, v242
	v_div_fmas_f32 v240, v240, v241, v244
	v_div_fixup_f32 v240, v240, v239, v71
	v_mul_f32_e32 v240, v79, v240
	v_med3_f32 v240, v240, s57, v194
	v_cvt_f16_f32_e32 v246, v240
	global_store_short v237, v245, s[100:101]
	global_store_short v237, v246, s[100:101] offset:32
	s_add_u32 s100, s98, 0x6e000
	s_addc_u32 s101, s99, 0
	v_mul_f32_e32 v238, 0xbfb8aa3b, v80
	v_exp_f32_e32 v238, v238
	s_nop 0
	v_add_f32_e32 v239, 1.0, v238
	v_div_scale_f32 v240, s[8:9], v239, v239, v80
	v_rcp_f32_e32 v241, v240
	v_div_scale_f32 v242, vcc, v80, v239, v80
	v_fma_f32 v243, -v240, v241, 1.0
	v_fmac_f32_e32 v241, v243, v241
	v_mul_f32_e32 v244, v242, v241
	v_fma_f32 v243, -v240, v244, v242
	v_fmac_f32_e32 v244, v243, v241
	v_fma_f32 v240, -v240, v244, v242
	v_div_fmas_f32 v240, v240, v241, v244
	v_div_fixup_f32 v240, v240, v239, v80
	v_mul_f32_e32 v240, v88, v240
	v_med3_f32 v240, v240, s57, v194
	v_cvt_f16_f32_e32 v245, v240
	v_mul_f32_e32 v238, 0xbfb8aa3b, v84
	v_exp_f32_e32 v238, v238
	s_nop 0
	v_add_f32_e32 v239, 1.0, v238
	v_div_scale_f32 v240, s[8:9], v239, v239, v84
	v_rcp_f32_e32 v241, v240
	v_div_scale_f32 v242, vcc, v84, v239, v84
	v_fma_f32 v243, -v240, v241, 1.0
	v_fmac_f32_e32 v241, v243, v241
	v_mul_f32_e32 v244, v242, v241
	v_fma_f32 v243, -v240, v244, v242
	v_fmac_f32_e32 v244, v243, v241
	v_fma_f32 v240, -v240, v244, v242
	v_div_fmas_f32 v240, v240, v241, v244
	v_div_fixup_f32 v240, v240, v239, v84
	v_mul_f32_e32 v240, v92, v240
	v_med3_f32 v240, v240, s57, v194
	v_cvt_f16_f32_e32 v246, v240
	global_store_short v237, v245, s[100:101]
	global_store_short v237, v246, s[100:101] offset:32
	s_add_u32 s100, s98, 0x6f600
	s_addc_u32 s101, s99, 0
	v_mul_f32_e32 v238, 0xbfb8aa3b, v81
	v_exp_f32_e32 v238, v238
	s_nop 0
	v_add_f32_e32 v239, 1.0, v238
	v_div_scale_f32 v240, s[8:9], v239, v239, v81
	v_rcp_f32_e32 v241, v240
	v_div_scale_f32 v242, vcc, v81, v239, v81
	v_fma_f32 v243, -v240, v241, 1.0
	v_fmac_f32_e32 v241, v243, v241
	v_mul_f32_e32 v244, v242, v241
	v_fma_f32 v243, -v240, v244, v242
	v_fmac_f32_e32 v244, v243, v241
	v_fma_f32 v240, -v240, v244, v242
	v_div_fmas_f32 v240, v240, v241, v244
	v_div_fixup_f32 v240, v240, v239, v81
	v_mul_f32_e32 v240, v89, v240
	v_med3_f32 v240, v240, s57, v194
	v_cvt_f16_f32_e32 v245, v240
	v_mul_f32_e32 v238, 0xbfb8aa3b, v85
	v_exp_f32_e32 v238, v238
	s_nop 0
	v_add_f32_e32 v239, 1.0, v238
	v_div_scale_f32 v240, s[8:9], v239, v239, v85
	v_rcp_f32_e32 v241, v240
	v_div_scale_f32 v242, vcc, v85, v239, v85
	v_fma_f32 v243, -v240, v241, 1.0
	v_fmac_f32_e32 v241, v243, v241
	v_mul_f32_e32 v244, v242, v241
	v_fma_f32 v243, -v240, v244, v242
	v_fmac_f32_e32 v244, v243, v241
	v_fma_f32 v240, -v240, v244, v242
	v_div_fmas_f32 v240, v240, v241, v244
	v_div_fixup_f32 v240, v240, v239, v85
	v_mul_f32_e32 v240, v93, v240
	v_med3_f32 v240, v240, s57, v194
	v_cvt_f16_f32_e32 v246, v240
	global_store_short v237, v245, s[100:101]
	global_store_short v237, v246, s[100:101] offset:32
	s_add_u32 s100, s98, 0x70c00
	s_addc_u32 s101, s99, 0
	v_mul_f32_e32 v238, 0xbfb8aa3b, v82
	v_exp_f32_e32 v238, v238
	s_nop 0
	v_add_f32_e32 v239, 1.0, v238
	v_div_scale_f32 v240, s[8:9], v239, v239, v82
	v_rcp_f32_e32 v241, v240
	v_div_scale_f32 v242, vcc, v82, v239, v82
	v_fma_f32 v243, -v240, v241, 1.0
	v_fmac_f32_e32 v241, v243, v241
	v_mul_f32_e32 v244, v242, v241
	v_fma_f32 v243, -v240, v244, v242
	v_fmac_f32_e32 v244, v243, v241
	v_fma_f32 v240, -v240, v244, v242
	v_div_fmas_f32 v240, v240, v241, v244
	v_div_fixup_f32 v240, v240, v239, v82
	v_mul_f32_e32 v240, v90, v240
	v_med3_f32 v240, v240, s57, v194
	v_cvt_f16_f32_e32 v245, v240
	v_mul_f32_e32 v238, 0xbfb8aa3b, v86
	v_exp_f32_e32 v238, v238
	s_nop 0
	v_add_f32_e32 v239, 1.0, v238
	v_div_scale_f32 v240, s[8:9], v239, v239, v86
	v_rcp_f32_e32 v241, v240
	v_div_scale_f32 v242, vcc, v86, v239, v86
	v_fma_f32 v243, -v240, v241, 1.0
	v_fmac_f32_e32 v241, v243, v241
	v_mul_f32_e32 v244, v242, v241
	v_fma_f32 v243, -v240, v244, v242
	v_fmac_f32_e32 v244, v243, v241
	v_fma_f32 v240, -v240, v244, v242
	v_div_fmas_f32 v240, v240, v241, v244
	v_div_fixup_f32 v240, v240, v239, v86
	v_mul_f32_e32 v240, v94, v240
	v_med3_f32 v240, v240, s57, v194
	v_cvt_f16_f32_e32 v246, v240
	global_store_short v237, v245, s[100:101]
	global_store_short v237, v246, s[100:101] offset:32
	s_add_u32 s100, s98, 0x72200
	s_addc_u32 s101, s99, 0
	v_mul_f32_e32 v238, 0xbfb8aa3b, v83
	v_exp_f32_e32 v238, v238
	s_nop 0
	v_add_f32_e32 v239, 1.0, v238
	v_div_scale_f32 v240, s[8:9], v239, v239, v83
	v_rcp_f32_e32 v241, v240
	v_div_scale_f32 v242, vcc, v83, v239, v83
	v_fma_f32 v243, -v240, v241, 1.0
	v_fmac_f32_e32 v241, v243, v241
	v_mul_f32_e32 v244, v242, v241
	v_fma_f32 v243, -v240, v244, v242
	v_fmac_f32_e32 v244, v243, v241
	v_fma_f32 v240, -v240, v244, v242
	v_div_fmas_f32 v240, v240, v241, v244
	v_div_fixup_f32 v240, v240, v239, v83
	v_mul_f32_e32 v240, v91, v240
	v_med3_f32 v240, v240, s57, v194
	v_cvt_f16_f32_e32 v245, v240
	v_mul_f32_e32 v238, 0xbfb8aa3b, v87
	v_exp_f32_e32 v238, v238
	s_nop 0
	v_add_f32_e32 v239, 1.0, v238
	v_div_scale_f32 v240, s[8:9], v239, v239, v87
	v_rcp_f32_e32 v241, v240
	v_div_scale_f32 v242, vcc, v87, v239, v87
	v_fma_f32 v243, -v240, v241, 1.0
	v_fmac_f32_e32 v241, v243, v241
	v_mul_f32_e32 v244, v242, v241
	v_fma_f32 v243, -v240, v244, v242
	v_fmac_f32_e32 v244, v243, v241
	v_fma_f32 v240, -v240, v244, v242
	v_div_fmas_f32 v240, v240, v241, v244
	v_div_fixup_f32 v240, v240, v239, v87
	v_mul_f32_e32 v240, v95, v240
	v_med3_f32 v240, v240, s57, v194
	v_cvt_f16_f32_e32 v246, v240
	global_store_short v237, v245, s[100:101]
	global_store_short v237, v246, s[100:101] offset:32
	s_add_u32 s100, s98, 0x84000
	s_addc_u32 s101, s99, 0
	v_mul_f32_e32 v238, 0xbfb8aa3b, v96
	v_exp_f32_e32 v238, v238
	s_nop 0
	v_add_f32_e32 v239, 1.0, v238
	v_div_scale_f32 v240, s[8:9], v239, v239, v96
	v_rcp_f32_e32 v241, v240
	v_div_scale_f32 v242, vcc, v96, v239, v96
	v_fma_f32 v243, -v240, v241, 1.0
	v_fmac_f32_e32 v241, v243, v241
	v_mul_f32_e32 v244, v242, v241
	v_fma_f32 v243, -v240, v244, v242
	v_fmac_f32_e32 v244, v243, v241
	v_fma_f32 v240, -v240, v244, v242
	v_div_fmas_f32 v240, v240, v241, v244
	v_div_fixup_f32 v240, v240, v239, v96
	v_mul_f32_e32 v240, v104, v240
	v_med3_f32 v240, v240, s57, v194
	v_cvt_f16_f32_e32 v245, v240
	v_mul_f32_e32 v238, 0xbfb8aa3b, v100
	v_exp_f32_e32 v238, v238
	s_nop 0
	v_add_f32_e32 v239, 1.0, v238
	v_div_scale_f32 v240, s[8:9], v239, v239, v100
	v_rcp_f32_e32 v241, v240
	v_div_scale_f32 v242, vcc, v100, v239, v100
	v_fma_f32 v243, -v240, v241, 1.0
	v_fmac_f32_e32 v241, v243, v241
	v_mul_f32_e32 v244, v242, v241
	v_fma_f32 v243, -v240, v244, v242
	v_fmac_f32_e32 v244, v243, v241
	v_fma_f32 v240, -v240, v244, v242
	v_div_fmas_f32 v240, v240, v241, v244
	v_div_fixup_f32 v240, v240, v239, v100
	v_mul_f32_e32 v240, v108, v240
	v_med3_f32 v240, v240, s57, v194
	v_cvt_f16_f32_e32 v246, v240
	global_store_short v237, v245, s[100:101]
	global_store_short v237, v246, s[100:101] offset:32
	s_add_u32 s100, s98, 0x85600
	s_addc_u32 s101, s99, 0
	v_mul_f32_e32 v238, 0xbfb8aa3b, v97
	v_exp_f32_e32 v238, v238
	s_nop 0
	v_add_f32_e32 v239, 1.0, v238
	v_div_scale_f32 v240, s[8:9], v239, v239, v97
	v_rcp_f32_e32 v241, v240
	v_div_scale_f32 v242, vcc, v97, v239, v97
	v_fma_f32 v243, -v240, v241, 1.0
	v_fmac_f32_e32 v241, v243, v241
	v_mul_f32_e32 v244, v242, v241
	v_fma_f32 v243, -v240, v244, v242
	v_fmac_f32_e32 v244, v243, v241
	v_fma_f32 v240, -v240, v244, v242
	v_div_fmas_f32 v240, v240, v241, v244
	v_div_fixup_f32 v240, v240, v239, v97
	v_mul_f32_e32 v240, v105, v240
	v_med3_f32 v240, v240, s57, v194
	v_cvt_f16_f32_e32 v245, v240
	v_mul_f32_e32 v238, 0xbfb8aa3b, v101
	v_exp_f32_e32 v238, v238
	s_nop 0
	v_add_f32_e32 v239, 1.0, v238
	v_div_scale_f32 v240, s[8:9], v239, v239, v101
	v_rcp_f32_e32 v241, v240
	v_div_scale_f32 v242, vcc, v101, v239, v101
	v_fma_f32 v243, -v240, v241, 1.0
	v_fmac_f32_e32 v241, v243, v241
	v_mul_f32_e32 v244, v242, v241
	v_fma_f32 v243, -v240, v244, v242
	v_fmac_f32_e32 v244, v243, v241
	v_fma_f32 v240, -v240, v244, v242
	v_div_fmas_f32 v240, v240, v241, v244
	v_div_fixup_f32 v240, v240, v239, v101
	v_mul_f32_e32 v240, v109, v240
	v_med3_f32 v240, v240, s57, v194
	v_cvt_f16_f32_e32 v246, v240
	global_store_short v237, v245, s[100:101]
	global_store_short v237, v246, s[100:101] offset:32
	s_add_u32 s100, s98, 0x86c00
	s_addc_u32 s101, s99, 0
	v_mul_f32_e32 v238, 0xbfb8aa3b, v98
	v_exp_f32_e32 v238, v238
	s_nop 0
	v_add_f32_e32 v239, 1.0, v238
	v_div_scale_f32 v240, s[8:9], v239, v239, v98
	v_rcp_f32_e32 v241, v240
	v_div_scale_f32 v242, vcc, v98, v239, v98
	v_fma_f32 v243, -v240, v241, 1.0
	v_fmac_f32_e32 v241, v243, v241
	v_mul_f32_e32 v244, v242, v241
	v_fma_f32 v243, -v240, v244, v242
	v_fmac_f32_e32 v244, v243, v241
	v_fma_f32 v240, -v240, v244, v242
	v_div_fmas_f32 v240, v240, v241, v244
	v_div_fixup_f32 v240, v240, v239, v98
	v_mul_f32_e32 v240, v106, v240
	v_med3_f32 v240, v240, s57, v194
	v_cvt_f16_f32_e32 v245, v240
	v_mul_f32_e32 v238, 0xbfb8aa3b, v102
	v_exp_f32_e32 v238, v238
	s_nop 0
	v_add_f32_e32 v239, 1.0, v238
	v_div_scale_f32 v240, s[8:9], v239, v239, v102
	v_rcp_f32_e32 v241, v240
	v_div_scale_f32 v242, vcc, v102, v239, v102
	v_fma_f32 v243, -v240, v241, 1.0
	v_fmac_f32_e32 v241, v243, v241
	v_mul_f32_e32 v244, v242, v241
	v_fma_f32 v243, -v240, v244, v242
	v_fmac_f32_e32 v244, v243, v241
	v_fma_f32 v240, -v240, v244, v242
	v_div_fmas_f32 v240, v240, v241, v244
	v_div_fixup_f32 v240, v240, v239, v102
	v_mul_f32_e32 v240, v110, v240
	v_med3_f32 v240, v240, s57, v194
	v_cvt_f16_f32_e32 v246, v240
	global_store_short v237, v245, s[100:101]
	global_store_short v237, v246, s[100:101] offset:32
	s_add_u32 s100, s98, 0x88200
	s_addc_u32 s101, s99, 0
	v_mul_f32_e32 v238, 0xbfb8aa3b, v99
	v_exp_f32_e32 v238, v238
	s_nop 0
	v_add_f32_e32 v239, 1.0, v238
	v_div_scale_f32 v240, s[8:9], v239, v239, v99
	v_rcp_f32_e32 v241, v240
	v_div_scale_f32 v242, vcc, v99, v239, v99
	v_fma_f32 v243, -v240, v241, 1.0
	v_fmac_f32_e32 v241, v243, v241
	v_mul_f32_e32 v244, v242, v241
	v_fma_f32 v243, -v240, v244, v242
	v_fmac_f32_e32 v244, v243, v241
	v_fma_f32 v240, -v240, v244, v242
	v_div_fmas_f32 v240, v240, v241, v244
	v_div_fixup_f32 v240, v240, v239, v99
	v_mul_f32_e32 v240, v107, v240
	v_med3_f32 v240, v240, s57, v194
	v_cvt_f16_f32_e32 v245, v240
	v_mul_f32_e32 v238, 0xbfb8aa3b, v103
	v_exp_f32_e32 v238, v238
	s_nop 0
	v_add_f32_e32 v239, 1.0, v238
	v_div_scale_f32 v240, s[8:9], v239, v239, v103
	v_rcp_f32_e32 v241, v240
	v_div_scale_f32 v242, vcc, v103, v239, v103
	v_fma_f32 v243, -v240, v241, 1.0
	v_fmac_f32_e32 v241, v243, v241
	v_mul_f32_e32 v244, v242, v241
	v_fma_f32 v243, -v240, v244, v242
	v_fmac_f32_e32 v244, v243, v241
	v_fma_f32 v240, -v240, v244, v242
	v_div_fmas_f32 v240, v240, v241, v244
	v_div_fixup_f32 v240, v240, v239, v103
	v_mul_f32_e32 v240, v111, v240
	v_med3_f32 v240, v240, s57, v194
	v_cvt_f16_f32_e32 v246, v240
	global_store_short v237, v245, s[100:101]
	global_store_short v237, v246, s[100:101] offset:32
	s_add_u32 s100, s98, 0x9a000
	s_addc_u32 s101, s99, 0
	v_mul_f32_e32 v238, 0xbfb8aa3b, v116
	v_exp_f32_e32 v238, v238
	s_nop 0
	v_add_f32_e32 v239, 1.0, v238
	v_div_scale_f32 v240, s[8:9], v239, v239, v116
	v_rcp_f32_e32 v241, v240
	v_div_scale_f32 v242, vcc, v116, v239, v116
	v_fma_f32 v243, -v240, v241, 1.0
	v_fmac_f32_e32 v241, v243, v241
	v_mul_f32_e32 v244, v242, v241
	v_fma_f32 v243, -v240, v244, v242
	v_fmac_f32_e32 v244, v243, v241
	v_fma_f32 v240, -v240, v244, v242
	v_div_fmas_f32 v240, v240, v241, v244
	v_div_fixup_f32 v240, v240, v239, v116
	v_mul_f32_e32 v240, v124, v240
	v_med3_f32 v240, v240, s57, v194
	v_cvt_f16_f32_e32 v245, v240
	v_mul_f32_e32 v238, 0xbfb8aa3b, v120
	v_exp_f32_e32 v238, v238
	s_nop 0
	v_add_f32_e32 v239, 1.0, v238
	v_div_scale_f32 v240, s[8:9], v239, v239, v120
	v_rcp_f32_e32 v241, v240
	v_div_scale_f32 v242, vcc, v120, v239, v120
	v_fma_f32 v243, -v240, v241, 1.0
	v_fmac_f32_e32 v241, v243, v241
	v_mul_f32_e32 v244, v242, v241
	v_fma_f32 v243, -v240, v244, v242
	v_fmac_f32_e32 v244, v243, v241
	v_fma_f32 v240, -v240, v244, v242
	v_div_fmas_f32 v240, v240, v241, v244
	v_div_fixup_f32 v240, v240, v239, v120
	v_mul_f32_e32 v240, v128, v240
	v_med3_f32 v240, v240, s57, v194
	v_cvt_f16_f32_e32 v246, v240
	global_store_short v237, v245, s[100:101]
	global_store_short v237, v246, s[100:101] offset:32
	s_add_u32 s100, s98, 0x9b600
	s_addc_u32 s101, s99, 0
	v_mul_f32_e32 v238, 0xbfb8aa3b, v117
	v_exp_f32_e32 v238, v238
	s_nop 0
	v_add_f32_e32 v239, 1.0, v238
	v_div_scale_f32 v240, s[8:9], v239, v239, v117
	v_rcp_f32_e32 v241, v240
	v_div_scale_f32 v242, vcc, v117, v239, v117
	v_fma_f32 v243, -v240, v241, 1.0
	v_fmac_f32_e32 v241, v243, v241
	v_mul_f32_e32 v244, v242, v241
	v_fma_f32 v243, -v240, v244, v242
	v_fmac_f32_e32 v244, v243, v241
	v_fma_f32 v240, -v240, v244, v242
	v_div_fmas_f32 v240, v240, v241, v244
	v_div_fixup_f32 v240, v240, v239, v117
	v_mul_f32_e32 v240, v125, v240
	v_med3_f32 v240, v240, s57, v194
	v_cvt_f16_f32_e32 v245, v240
	v_mul_f32_e32 v238, 0xbfb8aa3b, v121
	v_exp_f32_e32 v238, v238
	s_nop 0
	v_add_f32_e32 v239, 1.0, v238
	v_div_scale_f32 v240, s[8:9], v239, v239, v121
	v_rcp_f32_e32 v241, v240
	v_div_scale_f32 v242, vcc, v121, v239, v121
	v_fma_f32 v243, -v240, v241, 1.0
	v_fmac_f32_e32 v241, v243, v241
	v_mul_f32_e32 v244, v242, v241
	v_fma_f32 v243, -v240, v244, v242
	v_fmac_f32_e32 v244, v243, v241
	v_fma_f32 v240, -v240, v244, v242
	v_div_fmas_f32 v240, v240, v241, v244
	v_div_fixup_f32 v240, v240, v239, v121
	v_mul_f32_e32 v240, v129, v240
	v_med3_f32 v240, v240, s57, v194
	v_cvt_f16_f32_e32 v246, v240
	global_store_short v237, v245, s[100:101]
	global_store_short v237, v246, s[100:101] offset:32
	s_add_u32 s100, s98, 0x9cc00
	s_addc_u32 s101, s99, 0
	v_mul_f32_e32 v238, 0xbfb8aa3b, v118
	v_exp_f32_e32 v238, v238
	s_nop 0
	v_add_f32_e32 v239, 1.0, v238
	v_div_scale_f32 v240, s[8:9], v239, v239, v118
	v_rcp_f32_e32 v241, v240
	v_div_scale_f32 v242, vcc, v118, v239, v118
	v_fma_f32 v243, -v240, v241, 1.0
	v_fmac_f32_e32 v241, v243, v241
	v_mul_f32_e32 v244, v242, v241
	v_fma_f32 v243, -v240, v244, v242
	v_fmac_f32_e32 v244, v243, v241
	v_fma_f32 v240, -v240, v244, v242
	v_div_fmas_f32 v240, v240, v241, v244
	v_div_fixup_f32 v240, v240, v239, v118
	v_mul_f32_e32 v240, v126, v240
	v_med3_f32 v240, v240, s57, v194
	v_cvt_f16_f32_e32 v245, v240
	v_mul_f32_e32 v238, 0xbfb8aa3b, v122
	v_exp_f32_e32 v238, v238
	s_nop 0
	v_add_f32_e32 v239, 1.0, v238
	v_div_scale_f32 v240, s[8:9], v239, v239, v122
	v_rcp_f32_e32 v241, v240
	v_div_scale_f32 v242, vcc, v122, v239, v122
	v_fma_f32 v243, -v240, v241, 1.0
	v_fmac_f32_e32 v241, v243, v241
	v_mul_f32_e32 v244, v242, v241
	v_fma_f32 v243, -v240, v244, v242
	v_fmac_f32_e32 v244, v243, v241
	v_fma_f32 v240, -v240, v244, v242
	v_div_fmas_f32 v240, v240, v241, v244
	v_div_fixup_f32 v240, v240, v239, v122
	v_mul_f32_e32 v240, v130, v240
	v_med3_f32 v240, v240, s57, v194
	v_cvt_f16_f32_e32 v246, v240
	global_store_short v237, v245, s[100:101]
	global_store_short v237, v246, s[100:101] offset:32
	s_add_u32 s100, s98, 0x9e200
	s_addc_u32 s101, s99, 0
	v_mul_f32_e32 v238, 0xbfb8aa3b, v119
	v_exp_f32_e32 v238, v238
	s_nop 0
	v_add_f32_e32 v239, 1.0, v238
	v_div_scale_f32 v240, s[8:9], v239, v239, v119
	v_rcp_f32_e32 v241, v240
	v_div_scale_f32 v242, vcc, v119, v239, v119
	v_fma_f32 v243, -v240, v241, 1.0
	v_fmac_f32_e32 v241, v243, v241
	v_mul_f32_e32 v244, v242, v241
	v_fma_f32 v243, -v240, v244, v242
	v_fmac_f32_e32 v244, v243, v241
	v_fma_f32 v240, -v240, v244, v242
	v_div_fmas_f32 v240, v240, v241, v244
	v_div_fixup_f32 v240, v240, v239, v119
	v_mul_f32_e32 v240, v127, v240
	v_med3_f32 v240, v240, s57, v194
	v_cvt_f16_f32_e32 v245, v240
	v_mul_f32_e32 v238, 0xbfb8aa3b, v123
	v_exp_f32_e32 v238, v238
	s_nop 0
	v_add_f32_e32 v239, 1.0, v238
	v_div_scale_f32 v240, s[8:9], v239, v239, v123
	v_rcp_f32_e32 v241, v240
	v_div_scale_f32 v242, vcc, v123, v239, v123
	v_fma_f32 v243, -v240, v241, 1.0
	v_fmac_f32_e32 v241, v243, v241
	v_mul_f32_e32 v244, v242, v241
	v_fma_f32 v243, -v240, v244, v242
	v_fmac_f32_e32 v244, v243, v241
	v_fma_f32 v240, -v240, v244, v242
	v_div_fmas_f32 v240, v240, v241, v244
	v_div_fixup_f32 v240, v240, v239, v123
	v_mul_f32_e32 v240, v131, v240
	v_med3_f32 v240, v240, s57, v194
	v_cvt_f16_f32_e32 v246, v240
	global_store_short v237, v245, s[100:101]
	global_store_short v237, v246, s[100:101] offset:32
	s_add_i32 s12, s12, s60
	s_lshr_b32 s4, s62, 1
	s_cmp_ge_i32 s12, s4
	s_cbranch_scc0 .LBB0_136

.LBB0_634:
	s_waitcnt lgkmcnt(0)
	s_sub_u32 s4, s0, s65
	s_lshl_b32 s4, s4, 8
	s_lshl_b32 s13, s65, 7
	s_add_u32 s12, s4, s13
	v_lshrrev_b32_e32 v238, 4, v182
	v_xor_b32_e32 v238, v238, v182
	v_and_b32_e32 v238, 7, v238
	v_lshlrev_b32_e32 v238, 4, v238
	v_lshrrev_b32_e32 v239, 3, v182
	v_lshrrev_b32_e32 v240, 6, v182
	v_lshl_or_b32 v224, v239, 11, v238
	v_readfirstlane_b32 s5, v240
	v_add_u32_e32 v225, 0x10000, v224
	v_add_u32_e32 v226, 0x20000, v224
	v_add_u32_e32 v227, 0x30000, v224
	v_add_u32_e32 v228, 0x40000, v224
	v_add_u32_e32 v229, 0x50000, v224
	v_add_u32_e32 v230, 0x60000, v224
	v_add_u32_e32 v231, 0x70000, v224
	v_and_b32_e32 v241, 15, v182
	v_bfe_u32 v242, v182, 4, 2
	v_bfe_u32 v243, v182, 1, 3
	v_xor_b32_e32 v244, v242, v243
	v_or_b32_e32 v245, 4, v242
	v_xor_b32_e32 v245, v245, v243
	v_lshlrev_b32_e32 v244, 4, v244
	v_lshlrev_b32_e32 v245, 4, v245
	v_lshl_or_b32 v244, v241, 7, v244
	v_lshl_or_b32 v245, v241, 7, v245
	v_bfe_u32 v246, v182, 7, 1
	v_bfe_u32 v247, v182, 6, 1
	v_lshl_add_u32 v233, v246, 14, v244
	v_lshl_add_u32 v234, v246, 14, v245
	v_lshl_add_u32 v235, v247, 13, v244
	v_lshl_add_u32 v236, v247, 13, v245
	v_lshlrev_b32_e32 v248, 2, v242
	v_lshl_or_b32 v248, v246, 7, v248
	v_mul_u32_u24_e32 v237, 0x1600, v248
	v_lshl_or_b32 v248, v247, 5, v241
	v_lshl_add_u32 v237, v248, 1, v237
	s_lshl_b32 s5, s5, 10
	s_lshl_b32 s4, s12, 11
	s_add_u32 s2, s40, s4
	s_addc_u32 s3, s41, 0
	s_lshl_b32 s4, s11, 18
	v_readlane_b32 s8, v250, 17
	v_readlane_b32 s9, v250, 18
	s_add_u32 s8, s8, s4
	s_addc_u32 s9, s9, 0
	s_mul_i32 s4, s12, 0x1600
	s_lshl_b32 s13, s11, 7
	s_add_u32 s4, s4, s13
	s_add_u32 s98, s30, s4
	s_addc_u32 s99, s31, 0
	v_mov_b32_e32 v0, 0
	v_mov_b32_e32 v1, v0
	v_mov_b32_e32 v2, v0
	v_mov_b32_e32 v3, v0
	v_mov_b32_e32 v4, v0
	v_mov_b32_e32 v5, v0
	v_mov_b32_e32 v6, v0
	v_mov_b32_e32 v7, v0
	v_mov_b32_e32 v8, v0
	v_mov_b32_e32 v9, v0
	v_mov_b32_e32 v10, v0
	v_mov_b32_e32 v11, v0
	v_mov_b32_e32 v12, v0
	v_mov_b32_e32 v13, v0
	v_mov_b32_e32 v14, v0
	v_mov_b32_e32 v15, v0
	v_mov_b32_e32 v16, v0
	v_mov_b32_e32 v17, v0
	v_mov_b32_e32 v18, v0
	v_mov_b32_e32 v19, v0
	v_mov_b32_e32 v20, v0
	v_mov_b32_e32 v21, v0
	v_mov_b32_e32 v22, v0
	v_mov_b32_e32 v23, v0
	v_mov_b32_e32 v24, v0
	v_mov_b32_e32 v25, v0
	v_mov_b32_e32 v26, v0
	v_mov_b32_e32 v27, v0
	v_mov_b32_e32 v28, v0
	v_mov_b32_e32 v29, v0
	v_mov_b32_e32 v30, v0
	v_mov_b32_e32 v31, v0
	v_mov_b32_e32 v32, v0
	v_mov_b32_e32 v33, v0
	v_mov_b32_e32 v34, v0
	v_mov_b32_e32 v35, v0
	v_mov_b32_e32 v36, v0
	v_mov_b32_e32 v37, v0
	v_mov_b32_e32 v38, v0
	v_mov_b32_e32 v39, v0
	v_mov_b32_e32 v40, v0
	v_mov_b32_e32 v41, v0
	v_mov_b32_e32 v42, v0
	v_mov_b32_e32 v43, v0
	v_mov_b32_e32 v44, v0
	v_mov_b32_e32 v45, v0
	v_mov_b32_e32 v46, v0
	v_mov_b32_e32 v47, v0
	v_mov_b32_e32 v48, v0
	v_mov_b32_e32 v49, v0
	v_mov_b32_e32 v50, v0
	v_mov_b32_e32 v51, v0
	v_mov_b32_e32 v52, v0
	v_mov_b32_e32 v53, v0
	v_mov_b32_e32 v54, v0
	v_mov_b32_e32 v55, v0
	v_mov_b32_e32 v56, v0
	v_mov_b32_e32 v57, v0
	v_mov_b32_e32 v58, v0
	v_mov_b32_e32 v59, v0
	v_mov_b32_e32 v60, v0
	v_mov_b32_e32 v61, v0
	v_mov_b32_e32 v62, v0
	v_mov_b32_e32 v63, v0
	v_mov_b32_e32 v64, v0
	v_mov_b32_e32 v65, v0
	v_mov_b32_e32 v66, v0
	v_mov_b32_e32 v67, v0
	v_mov_b32_e32 v68, v0
	v_mov_b32_e32 v69, v0
	v_mov_b32_e32 v70, v0
	v_mov_b32_e32 v71, v0
	v_mov_b32_e32 v72, v0
	v_mov_b32_e32 v73, v0
	v_mov_b32_e32 v74, v0
	v_mov_b32_e32 v75, v0
	v_mov_b32_e32 v76, v0
	v_mov_b32_e32 v77, v0
	v_mov_b32_e32 v78, v0
	v_mov_b32_e32 v79, v0
	v_mov_b32_e32 v80, v0
	v_mov_b32_e32 v81, v0
	v_mov_b32_e32 v82, v0
	v_mov_b32_e32 v83, v0
	v_mov_b32_e32 v84, v0
	v_mov_b32_e32 v85, v0
	v_mov_b32_e32 v86, v0
	v_mov_b32_e32 v87, v0
	v_mov_b32_e32 v88, v0
	v_mov_b32_e32 v89, v0
	v_mov_b32_e32 v90, v0
	v_mov_b32_e32 v91, v0
	v_mov_b32_e32 v92, v0
	v_mov_b32_e32 v93, v0
	v_mov_b32_e32 v94, v0
	v_mov_b32_e32 v95, v0
	v_mov_b32_e32 v96, v0
	v_mov_b32_e32 v97, v0
	v_mov_b32_e32 v98, v0
	v_mov_b32_e32 v99, v0
	v_mov_b32_e32 v100, v0
	v_mov_b32_e32 v101, v0
	v_mov_b32_e32 v102, v0
	v_mov_b32_e32 v103, v0
	v_mov_b32_e32 v104, v0
	v_mov_b32_e32 v105, v0
	v_mov_b32_e32 v106, v0
	v_mov_b32_e32 v107, v0
	v_mov_b32_e32 v108, v0
	v_mov_b32_e32 v109, v0
	v_mov_b32_e32 v110, v0
	v_mov_b32_e32 v111, v0
	v_mov_b32_e32 v116, v0
	v_mov_b32_e32 v117, v0
	v_mov_b32_e32 v118, v0
	v_mov_b32_e32 v119, v0
	v_mov_b32_e32 v120, v0
	v_mov_b32_e32 v121, v0
	v_mov_b32_e32 v122, v0
	v_mov_b32_e32 v123, v0
	v_mov_b32_e32 v124, v0
	v_mov_b32_e32 v125, v0
	v_mov_b32_e32 v126, v0
	v_mov_b32_e32 v127, v0
	v_mov_b32_e32 v128, v0
	v_mov_b32_e32 v129, v0
	v_mov_b32_e32 v130, v0
	v_mov_b32_e32 v131, v0
	s_movk_i32 s14, 16
.Lg3_sw2:
	s_barrier
	s_add_u32 m0, s5, 0x0
	s_nop 0
	global_load_lds_dwordx4 v224, s[2:3]
	s_add_u32 m0, s5, 0x1000
	s_nop 0
	global_load_lds_dwordx4 v225, s[2:3]
	s_add_u32 m0, s5, 0x2000
	s_nop 0
	global_load_lds_dwordx4 v226, s[2:3]
	s_add_u32 m0, s5, 0x3000
	s_nop 0
	global_load_lds_dwordx4 v227, s[2:3]
	s_add_u32 m0, s5, 0x4000
	s_nop 0
	global_load_lds_dwordx4 v228, s[2:3]
	s_add_u32 m0, s5, 0x5000
	s_nop 0
	global_load_lds_dwordx4 v229, s[2:3]
	s_add_u32 m0, s5, 0x6000
	s_nop 0
	global_load_lds_dwordx4 v230, s[2:3]
	s_add_u32 m0, s5, 0x7000
	s_nop 0
	global_load_lds_dwordx4 v231, s[2:3]
	s_add_u32 m0, s5, 0x8000
	s_nop 0
	global_load_lds_dwordx4 v224, s[8:9]
	s_add_u32 m0, s5, 0x9000
	s_nop 0
	global_load_lds_dwordx4 v225, s[8:9]
	s_add_u32 m0, s5, 0xa000
	s_nop 0
	global_load_lds_dwordx4 v226, s[8:9]
	s_add_u32 m0, s5, 0xb000
	s_nop 0
	global_load_lds_dwordx4 v227, s[8:9]
	s_add_u32 s2, s2, 0x80
	s_addc_u32 s3, s3, 0
	s_add_u32 s8, s8, 0x80
	s_addc_u32 s9, s9, 0
	s_waitcnt vmcnt(0)
	s_barrier
	ds_read_b128 v[164:167], v235 offset:32768
	ds_read_b128 v[168:171], v235 offset:34816
	ds_read_b128 v[172:175], v235 offset:36864
	ds_read_b128 v[176:179], v235 offset:38912
	ds_read_b128 v[132:135], v233 offset:0
	ds_read_b128 v[136:139], v233 offset:2048
	ds_read_b128 v[140:143], v233 offset:4096
	ds_read_b128 v[144:147], v233 offset:6144
	ds_read_b128 v[148:151], v233 offset:8192
	ds_read_b128 v[152:155], v233 offset:10240
	ds_read_b128 v[156:159], v233 offset:12288
	ds_read_b128 v[160:163], v233 offset:14336
	s_waitcnt lgkmcnt(7)
	v_mfma_f32_16x16x32_f16 v[0:3], v[132:135], v[164:167], v[0:3]
	v_mfma_f32_16x16x32_f16 v[4:7], v[132:135], v[168:171], v[4:7]
	v_mfma_f32_16x16x32_f16 v[8:11], v[132:135], v[172:175], v[8:11]
	v_mfma_f32_16x16x32_f16 v[12:15], v[132:135], v[176:179], v[12:15]
	s_waitcnt lgkmcnt(6)
	v_mfma_f32_16x16x32_f16 v[16:19], v[136:139], v[164:167], v[16:19]
	v_mfma_f32_16x16x32_f16 v[20:23], v[136:139], v[168:171], v[20:23]
	v_mfma_f32_16x16x32_f16 v[24:27], v[136:139], v[172:175], v[24:27]
	v_mfma_f32_16x16x32_f16 v[28:31], v[136:139], v[176:179], v[28:31]
	s_waitcnt lgkmcnt(5)
	v_mfma_f32_16x16x32_f16 v[32:35], v[140:143], v[164:167], v[32:35]
	v_mfma_f32_16x16x32_f16 v[36:39], v[140:143], v[168:171], v[36:39]
	v_mfma_f32_16x16x32_f16 v[40:43], v[140:143], v[172:175], v[40:43]
	v_mfma_f32_16x16x32_f16 v[44:47], v[140:143], v[176:179], v[44:47]
	s_waitcnt lgkmcnt(4)
	v_mfma_f32_16x16x32_f16 v[48:51], v[144:147], v[164:167], v[48:51]
	v_mfma_f32_16x16x32_f16 v[52:55], v[144:147], v[168:171], v[52:55]
	v_mfma_f32_16x16x32_f16 v[56:59], v[144:147], v[172:175], v[56:59]
	v_mfma_f32_16x16x32_f16 v[60:63], v[144:147], v[176:179], v[60:63]
	s_waitcnt lgkmcnt(3)
	v_mfma_f32_16x16x32_f16 v[64:67], v[148:151], v[164:167], v[64:67]
	v_mfma_f32_16x16x32_f16 v[68:71], v[148:151], v[168:171], v[68:71]
	v_mfma_f32_16x16x32_f16 v[72:75], v[148:151], v[172:175], v[72:75]
	v_mfma_f32_16x16x32_f16 v[76:79], v[148:151], v[176:179], v[76:79]
	s_waitcnt lgkmcnt(2)
	v_mfma_f32_16x16x32_f16 v[80:83], v[152:155], v[164:167], v[80:83]
	v_mfma_f32_16x16x32_f16 v[84:87], v[152:155], v[168:171], v[84:87]
	v_mfma_f32_16x16x32_f16 v[88:91], v[152:155], v[172:175], v[88:91]
	v_mfma_f32_16x16x32_f16 v[92:95], v[152:155], v[176:179], v[92:95]
	s_waitcnt lgkmcnt(1)
	v_mfma_f32_16x16x32_f16 v[96:99], v[156:159], v[164:167], v[96:99]
	v_mfma_f32_16x16x32_f16 v[100:103], v[156:159], v[168:171], v[100:103]
	v_mfma_f32_16x16x32_f16 v[104:107], v[156:159], v[172:175], v[104:107]
	v_mfma_f32_16x16x32_f16 v[108:111], v[156:159], v[176:179], v[108:111]
	s_waitcnt lgkmcnt(0)
	v_mfma_f32_16x16x32_f16 v[116:119], v[160:163], v[164:167], v[116:119]
	v_mfma_f32_16x16x32_f16 v[120:123], v[160:163], v[168:171], v[120:123]
	v_mfma_f32_16x16x32_f16 v[124:127], v[160:163], v[172:175], v[124:127]
	v_mfma_f32_16x16x32_f16 v[128:131], v[160:163], v[176:179], v[128:131]
	ds_read_b128 v[164:167], v236 offset:32768
	ds_read_b128 v[168:171], v236 offset:34816
	ds_read_b128 v[172:175], v236 offset:36864
	ds_read_b128 v[176:179], v236 offset:38912
	ds_read_b128 v[132:135], v234 offset:0
	ds_read_b128 v[136:139], v234 offset:2048
	ds_read_b128 v[140:143], v234 offset:4096
	ds_read_b128 v[144:147], v234 offset:6144
	ds_read_b128 v[148:151], v234 offset:8192
	ds_read_b128 v[152:155], v234 offset:10240
	ds_read_b128 v[156:159], v234 offset:12288
	ds_read_b128 v[160:163], v234 offset:14336
	s_waitcnt lgkmcnt(7)
	v_mfma_f32_16x16x32_f16 v[0:3], v[132:135], v[164:167], v[0:3]
	v_mfma_f32_16x16x32_f16 v[4:7], v[132:135], v[168:171], v[4:7]
	v_mfma_f32_16x16x32_f16 v[8:11], v[132:135], v[172:175], v[8:11]
	v_mfma_f32_16x16x32_f16 v[12:15], v[132:135], v[176:179], v[12:15]
	s_waitcnt lgkmcnt(6)
	v_mfma_f32_16x16x32_f16 v[16:19], v[136:139], v[164:167], v[16:19]
	v_mfma_f32_16x16x32_f16 v[20:23], v[136:139], v[168:171], v[20:23]
	v_mfma_f32_16x16x32_f16 v[24:27], v[136:139], v[172:175], v[24:27]
	v_mfma_f32_16x16x32_f16 v[28:31], v[136:139], v[176:179], v[28:31]
	s_waitcnt lgkmcnt(5)
	v_mfma_f32_16x16x32_f16 v[32:35], v[140:143], v[164:167], v[32:35]
	v_mfma_f32_16x16x32_f16 v[36:39], v[140:143], v[168:171], v[36:39]
	v_mfma_f32_16x16x32_f16 v[40:43], v[140:143], v[172:175], v[40:43]
	v_mfma_f32_16x16x32_f16 v[44:47], v[140:143], v[176:179], v[44:47]
	s_waitcnt lgkmcnt(4)
	v_mfma_f32_16x16x32_f16 v[48:51], v[144:147], v[164:167], v[48:51]
	v_mfma_f32_16x16x32_f16 v[52:55], v[144:147], v[168:171], v[52:55]
	v_mfma_f32_16x16x32_f16 v[56:59], v[144:147], v[172:175], v[56:59]
	v_mfma_f32_16x16x32_f16 v[60:63], v[144:147], v[176:179], v[60:63]
	s_waitcnt lgkmcnt(3)
	v_mfma_f32_16x16x32_f16 v[64:67], v[148:151], v[164:167], v[64:67]
	v_mfma_f32_16x16x32_f16 v[68:71], v[148:151], v[168:171], v[68:71]
	v_mfma_f32_16x16x32_f16 v[72:75], v[148:151], v[172:175], v[72:75]
	v_mfma_f32_16x16x32_f16 v[76:79], v[148:151], v[176:179], v[76:79]
	s_waitcnt lgkmcnt(2)
	v_mfma_f32_16x16x32_f16 v[80:83], v[152:155], v[164:167], v[80:83]
	v_mfma_f32_16x16x32_f16 v[84:87], v[152:155], v[168:171], v[84:87]
	v_mfma_f32_16x16x32_f16 v[88:91], v[152:155], v[172:175], v[88:91]
	v_mfma_f32_16x16x32_f16 v[92:95], v[152:155], v[176:179], v[92:95]
	s_waitcnt lgkmcnt(1)
	v_mfma_f32_16x16x32_f16 v[96:99], v[156:159], v[164:167], v[96:99]
	v_mfma_f32_16x16x32_f16 v[100:103], v[156:159], v[168:171], v[100:103]
	v_mfma_f32_16x16x32_f16 v[104:107], v[156:159], v[172:175], v[104:107]
	v_mfma_f32_16x16x32_f16 v[108:111], v[156:159], v[176:179], v[108:111]
	s_waitcnt lgkmcnt(0)
	v_mfma_f32_16x16x32_f16 v[116:119], v[160:163], v[164:167], v[116:119]
	v_mfma_f32_16x16x32_f16 v[120:123], v[160:163], v[168:171], v[120:123]
	v_mfma_f32_16x16x32_f16 v[124:127], v[160:163], v[172:175], v[124:127]
	v_mfma_f32_16x16x32_f16 v[128:131], v[160:163], v[176:179], v[128:131]
	s_sub_u32 s14, s14, 1
	s_cmp_lg_u32 s14, 0
	s_cbranch_scc1 .Lg3_sw2
	s_nop 7
	s_mov_b64 s[100:101], s[98:99]
	v_mul_f32_e32 v238, 0xbfb8aa3b, v0
	v_exp_f32_e32 v238, v238
	s_nop 0
	v_add_f32_e32 v239, 1.0, v238
	v_div_scale_f32 v240, s[2:3], v239, v239, v0
	v_rcp_f32_e32 v241, v240
	v_div_scale_f32 v242, vcc, v0, v239, v0
	v_fma_f32 v243, -v240, v241, 1.0
	v_fmac_f32_e32 v241, v243, v241
	v_mul_f32_e32 v244, v242, v241
	v_fma_f32 v243, -v240, v244, v242
	v_fmac_f32_e32 v244, v243, v241
	v_fma_f32 v240, -v240, v244, v242
	v_div_fmas_f32 v240, v240, v241, v244
	v_div_fixup_f32 v240, v240, v239, v0
	v_mul_f32_e32 v240, v8, v240
	v_med3_f32 v240, v240, s57, v194
	v_cvt_f16_f32_e32 v245, v240
	v_mul_f32_e32 v238, 0xbfb8aa3b, v4
	v_exp_f32_e32 v238, v238
	s_nop 0
	v_add_f32_e32 v239, 1.0, v238
	v_div_scale_f32 v240, s[2:3], v239, v239, v4
	v_rcp_f32_e32 v241, v240
	v_div_scale_f32 v242, vcc, v4, v239, v4
	v_fma_f32 v243, -v240, v241, 1.0
	v_fmac_f32_e32 v241, v243, v241
	v_mul_f32_e32 v244, v242, v241
	v_fma_f32 v243, -v240, v244, v242
	v_fmac_f32_e32 v244, v243, v241
	v_fma_f32 v240, -v240, v244, v242
	v_div_fmas_f32 v240, v240, v241, v244
	v_div_fixup_f32 v240, v240, v239, v4
	v_mul_f32_e32 v240, v12, v240
	v_med3_f32 v240, v240, s57, v194
	v_cvt_f16_f32_e32 v246, v240
	global_store_short v237, v245, s[100:101]
	global_store_short v237, v246, s[100:101] offset:32
	s_add_u32 s100, s98, 0x1600
	s_addc_u32 s101, s99, 0
	v_mul_f32_e32 v238, 0xbfb8aa3b, v1
	v_exp_f32_e32 v238, v238
	s_nop 0
	v_add_f32_e32 v239, 1.0, v238
	v_div_scale_f32 v240, s[2:3], v239, v239, v1
	v_rcp_f32_e32 v241, v240
	v_div_scale_f32 v242, vcc, v1, v239, v1
	v_fma_f32 v243, -v240, v241, 1.0
	v_fmac_f32_e32 v241, v243, v241
	v_mul_f32_e32 v244, v242, v241
	v_fma_f32 v243, -v240, v244, v242
	v_fmac_f32_e32 v244, v243, v241
	v_fma_f32 v240, -v240, v244, v242
	v_div_fmas_f32 v240, v240, v241, v244
	v_div_fixup_f32 v240, v240, v239, v1
	v_mul_f32_e32 v240, v9, v240
	v_med3_f32 v240, v240, s57, v194
	v_cvt_f16_f32_e32 v245, v240
	v_mul_f32_e32 v238, 0xbfb8aa3b, v5
	v_exp_f32_e32 v238, v238
	s_nop 0
	v_add_f32_e32 v239, 1.0, v238
	v_div_scale_f32 v240, s[2:3], v239, v239, v5
	v_rcp_f32_e32 v241, v240
	v_div_scale_f32 v242, vcc, v5, v239, v5
	v_fma_f32 v243, -v240, v241, 1.0
	v_fmac_f32_e32 v241, v243, v241
	v_mul_f32_e32 v244, v242, v241
	v_fma_f32 v243, -v240, v244, v242
	v_fmac_f32_e32 v244, v243, v241
	v_fma_f32 v240, -v240, v244, v242
	v_div_fmas_f32 v240, v240, v241, v244
	v_div_fixup_f32 v240, v240, v239, v5
	v_mul_f32_e32 v240, v13, v240
	v_med3_f32 v240, v240, s57, v194
	v_cvt_f16_f32_e32 v246, v240
	global_store_short v237, v245, s[100:101]
	global_store_short v237, v246, s[100:101] offset:32
	s_add_u32 s100, s98, 0x2c00
	s_addc_u32 s101, s99, 0
	v_mul_f32_e32 v238, 0xbfb8aa3b, v2
	v_exp_f32_e32 v238, v238
	s_nop 0
	v_add_f32_e32 v239, 1.0, v238
	v_div_scale_f32 v240, s[2:3], v239, v239, v2
	v_rcp_f32_e32 v241, v240
	v_div_scale_f32 v242, vcc, v2, v239, v2
	v_fma_f32 v243, -v240, v241, 1.0
	v_fmac_f32_e32 v241, v243, v241
	v_mul_f32_e32 v244, v242, v241
	v_fma_f32 v243, -v240, v244, v242
	v_fmac_f32_e32 v244, v243, v241
	v_fma_f32 v240, -v240, v244, v242
	v_div_fmas_f32 v240, v240, v241, v244
	v_div_fixup_f32 v240, v240, v239, v2
	v_mul_f32_e32 v240, v10, v240
	v_med3_f32 v240, v240, s57, v194
	v_cvt_f16_f32_e32 v245, v240
	v_mul_f32_e32 v238, 0xbfb8aa3b, v6
	v_exp_f32_e32 v238, v238
	s_nop 0
	v_add_f32_e32 v239, 1.0, v238
	v_div_scale_f32 v240, s[2:3], v239, v239, v6
	v_rcp_f32_e32 v241, v240
	v_div_scale_f32 v242, vcc, v6, v239, v6
	v_fma_f32 v243, -v240, v241, 1.0
	v_fmac_f32_e32 v241, v243, v241
	v_mul_f32_e32 v244, v242, v241
	v_fma_f32 v243, -v240, v244, v242
	v_fmac_f32_e32 v244, v243, v241
	v_fma_f32 v240, -v240, v244, v242
	v_div_fmas_f32 v240, v240, v241, v244
	v_div_fixup_f32 v240, v240, v239, v6
	v_mul_f32_e32 v240, v14, v240
	v_med3_f32 v240, v240, s57, v194
	v_cvt_f16_f32_e32 v246, v240
	global_store_short v237, v245, s[100:101]
	global_store_short v237, v246, s[100:101] offset:32
	s_add_u32 s100, s98, 0x4200
	s_addc_u32 s101, s99, 0
	v_mul_f32_e32 v238, 0xbfb8aa3b, v3
	v_exp_f32_e32 v238, v238
	s_nop 0
	v_add_f32_e32 v239, 1.0, v238
	v_div_scale_f32 v240, s[2:3], v239, v239, v3
	v_rcp_f32_e32 v241, v240
	v_div_scale_f32 v242, vcc, v3, v239, v3
	v_fma_f32 v243, -v240, v241, 1.0
	v_fmac_f32_e32 v241, v243, v241
	v_mul_f32_e32 v244, v242, v241
	v_fma_f32 v243, -v240, v244, v242
	v_fmac_f32_e32 v244, v243, v241
	v_fma_f32 v240, -v240, v244, v242
	v_div_fmas_f32 v240, v240, v241, v244
	v_div_fixup_f32 v240, v240, v239, v3
	v_mul_f32_e32 v240, v11, v240
	v_med3_f32 v240, v240, s57, v194
	v_cvt_f16_f32_e32 v245, v240
	v_mul_f32_e32 v238, 0xbfb8aa3b, v7
	v_exp_f32_e32 v238, v238
	s_nop 0
	v_add_f32_e32 v239, 1.0, v238
	v_div_scale_f32 v240, s[2:3], v239, v239, v7
	v_rcp_f32_e32 v241, v240
	v_div_scale_f32 v242, vcc, v7, v239, v7
	v_fma_f32 v243, -v240, v241, 1.0
	v_fmac_f32_e32 v241, v243, v241
	v_mul_f32_e32 v244, v242, v241
	v_fma_f32 v243, -v240, v244, v242
	v_fmac_f32_e32 v244, v243, v241
	v_fma_f32 v240, -v240, v244, v242
	v_div_fmas_f32 v240, v240, v241, v244
	v_div_fixup_f32 v240, v240, v239, v7
	v_mul_f32_e32 v240, v15, v240
	v_med3_f32 v240, v240, s57, v194
	v_cvt_f16_f32_e32 v246, v240
	global_store_short v237, v245, s[100:101]
	global_store_short v237, v246, s[100:101] offset:32
	s_add_u32 s100, s98, 0x16000
	s_addc_u32 s101, s99, 0
	v_mul_f32_e32 v238, 0xbfb8aa3b, v16
	v_exp_f32_e32 v238, v238
	s_nop 0
	v_add_f32_e32 v239, 1.0, v238
	v_div_scale_f32 v240, s[2:3], v239, v239, v16
	v_rcp_f32_e32 v241, v240
	v_div_scale_f32 v242, vcc, v16, v239, v16
	v_fma_f32 v243, -v240, v241, 1.0
	v_fmac_f32_e32 v241, v243, v241
	v_mul_f32_e32 v244, v242, v241
	v_fma_f32 v243, -v240, v244, v242
	v_fmac_f32_e32 v244, v243, v241
	v_fma_f32 v240, -v240, v244, v242
	v_div_fmas_f32 v240, v240, v241, v244
	v_div_fixup_f32 v240, v240, v239, v16
	v_mul_f32_e32 v240, v24, v240
	v_med3_f32 v240, v240, s57, v194
	v_cvt_f16_f32_e32 v245, v240
	v_mul_f32_e32 v238, 0xbfb8aa3b, v20
	v_exp_f32_e32 v238, v238
	s_nop 0
	v_add_f32_e32 v239, 1.0, v238
	v_div_scale_f32 v240, s[2:3], v239, v239, v20
	v_rcp_f32_e32 v241, v240
	v_div_scale_f32 v242, vcc, v20, v239, v20
	v_fma_f32 v243, -v240, v241, 1.0
	v_fmac_f32_e32 v241, v243, v241
	v_mul_f32_e32 v244, v242, v241
	v_fma_f32 v243, -v240, v244, v242
	v_fmac_f32_e32 v244, v243, v241
	v_fma_f32 v240, -v240, v244, v242
	v_div_fmas_f32 v240, v240, v241, v244
	v_div_fixup_f32 v240, v240, v239, v20
	v_mul_f32_e32 v240, v28, v240
	v_med3_f32 v240, v240, s57, v194
	v_cvt_f16_f32_e32 v246, v240
	global_store_short v237, v245, s[100:101]
	global_store_short v237, v246, s[100:101] offset:32
	s_add_u32 s100, s98, 0x17600
	s_addc_u32 s101, s99, 0
	v_mul_f32_e32 v238, 0xbfb8aa3b, v17
	v_exp_f32_e32 v238, v238
	s_nop 0
	v_add_f32_e32 v239, 1.0, v238
	v_div_scale_f32 v240, s[2:3], v239, v239, v17
	v_rcp_f32_e32 v241, v240
	v_div_scale_f32 v242, vcc, v17, v239, v17
	v_fma_f32 v243, -v240, v241, 1.0
	v_fmac_f32_e32 v241, v243, v241
	v_mul_f32_e32 v244, v242, v241
	v_fma_f32 v243, -v240, v244, v242
	v_fmac_f32_e32 v244, v243, v241
	v_fma_f32 v240, -v240, v244, v242
	v_div_fmas_f32 v240, v240, v241, v244
	v_div_fixup_f32 v240, v240, v239, v17
	v_mul_f32_e32 v240, v25, v240
	v_med3_f32 v240, v240, s57, v194
	v_cvt_f16_f32_e32 v245, v240
	v_mul_f32_e32 v238, 0xbfb8aa3b, v21
	v_exp_f32_e32 v238, v238
	s_nop 0
	v_add_f32_e32 v239, 1.0, v238
	v_div_scale_f32 v240, s[2:3], v239, v239, v21
	v_rcp_f32_e32 v241, v240
	v_div_scale_f32 v242, vcc, v21, v239, v21
	v_fma_f32 v243, -v240, v241, 1.0
	v_fmac_f32_e32 v241, v243, v241
	v_mul_f32_e32 v244, v242, v241
	v_fma_f32 v243, -v240, v244, v242
	v_fmac_f32_e32 v244, v243, v241
	v_fma_f32 v240, -v240, v244, v242
	v_div_fmas_f32 v240, v240, v241, v244
	v_div_fixup_f32 v240, v240, v239, v21
	v_mul_f32_e32 v240, v29, v240
	v_med3_f32 v240, v240, s57, v194
	v_cvt_f16_f32_e32 v246, v240
	global_store_short v237, v245, s[100:101]
	global_store_short v237, v246, s[100:101] offset:32
	s_add_u32 s100, s98, 0x18c00
	s_addc_u32 s101, s99, 0
	v_mul_f32_e32 v238, 0xbfb8aa3b, v18
	v_exp_f32_e32 v238, v238
	s_nop 0
	v_add_f32_e32 v239, 1.0, v238
	v_div_scale_f32 v240, s[2:3], v239, v239, v18
	v_rcp_f32_e32 v241, v240
	v_div_scale_f32 v242, vcc, v18, v239, v18
	v_fma_f32 v243, -v240, v241, 1.0
	v_fmac_f32_e32 v241, v243, v241
	v_mul_f32_e32 v244, v242, v241
	v_fma_f32 v243, -v240, v244, v242
	v_fmac_f32_e32 v244, v243, v241
	v_fma_f32 v240, -v240, v244, v242
	v_div_fmas_f32 v240, v240, v241, v244
	v_div_fixup_f32 v240, v240, v239, v18
	v_mul_f32_e32 v240, v26, v240
	v_med3_f32 v240, v240, s57, v194
	v_cvt_f16_f32_e32 v245, v240
	v_mul_f32_e32 v238, 0xbfb8aa3b, v22
	v_exp_f32_e32 v238, v238
	s_nop 0
	v_add_f32_e32 v239, 1.0, v238
	v_div_scale_f32 v240, s[2:3], v239, v239, v22
	v_rcp_f32_e32 v241, v240
	v_div_scale_f32 v242, vcc, v22, v239, v22
	v_fma_f32 v243, -v240, v241, 1.0
	v_fmac_f32_e32 v241, v243, v241
	v_mul_f32_e32 v244, v242, v241
	v_fma_f32 v243, -v240, v244, v242
	v_fmac_f32_e32 v244, v243, v241
	v_fma_f32 v240, -v240, v244, v242
	v_div_fmas_f32 v240, v240, v241, v244
	v_div_fixup_f32 v240, v240, v239, v22
	v_mul_f32_e32 v240, v30, v240
	v_med3_f32 v240, v240, s57, v194
	v_cvt_f16_f32_e32 v246, v240
	global_store_short v237, v245, s[100:101]
	global_store_short v237, v246, s[100:101] offset:32
	s_add_u32 s100, s98, 0x1a200
	s_addc_u32 s101, s99, 0
	v_mul_f32_e32 v238, 0xbfb8aa3b, v19
	v_exp_f32_e32 v238, v238
	s_nop 0
	v_add_f32_e32 v239, 1.0, v238
	v_div_scale_f32 v240, s[2:3], v239, v239, v19
	v_rcp_f32_e32 v241, v240
	v_div_scale_f32 v242, vcc, v19, v239, v19
	v_fma_f32 v243, -v240, v241, 1.0
	v_fmac_f32_e32 v241, v243, v241
	v_mul_f32_e32 v244, v242, v241
	v_fma_f32 v243, -v240, v244, v242
	v_fmac_f32_e32 v244, v243, v241
	v_fma_f32 v240, -v240, v244, v242
	v_div_fmas_f32 v240, v240, v241, v244
	v_div_fixup_f32 v240, v240, v239, v19
	v_mul_f32_e32 v240, v27, v240
	v_med3_f32 v240, v240, s57, v194
	v_cvt_f16_f32_e32 v245, v240
	v_mul_f32_e32 v238, 0xbfb8aa3b, v23
	v_exp_f32_e32 v238, v238
	s_nop 0
	v_add_f32_e32 v239, 1.0, v238
	v_div_scale_f32 v240, s[2:3], v239, v239, v23
	v_rcp_f32_e32 v241, v240
	v_div_scale_f32 v242, vcc, v23, v239, v23
	v_fma_f32 v243, -v240, v241, 1.0
	v_fmac_f32_e32 v241, v243, v241
	v_mul_f32_e32 v244, v242, v241
	v_fma_f32 v243, -v240, v244, v242
	v_fmac_f32_e32 v244, v243, v241
	v_fma_f32 v240, -v240, v244, v242
	v_div_fmas_f32 v240, v240, v241, v244
	v_div_fixup_f32 v240, v240, v239, v23
	v_mul_f32_e32 v240, v31, v240
	v_med3_f32 v240, v240, s57, v194
	v_cvt_f16_f32_e32 v246, v240
	global_store_short v237, v245, s[100:101]
	global_store_short v237, v246, s[100:101] offset:32
	s_add_u32 s100, s98, 0x2c000
	s_addc_u32 s101, s99, 0
	v_mul_f32_e32 v238, 0xbfb8aa3b, v32
	v_exp_f32_e32 v238, v238
	s_nop 0
	v_add_f32_e32 v239, 1.0, v238
	v_div_scale_f32 v240, s[2:3], v239, v239, v32
	v_rcp_f32_e32 v241, v240
	v_div_scale_f32 v242, vcc, v32, v239, v32
	v_fma_f32 v243, -v240, v241, 1.0
	v_fmac_f32_e32 v241, v243, v241
	v_mul_f32_e32 v244, v242, v241
	v_fma_f32 v243, -v240, v244, v242
	v_fmac_f32_e32 v244, v243, v241
	v_fma_f32 v240, -v240, v244, v242
	v_div_fmas_f32 v240, v240, v241, v244
	v_div_fixup_f32 v240, v240, v239, v32
	v_mul_f32_e32 v240, v40, v240
	v_med3_f32 v240, v240, s57, v194
	v_cvt_f16_f32_e32 v245, v240
	v_mul_f32_e32 v238, 0xbfb8aa3b, v36
	v_exp_f32_e32 v238, v238
	s_nop 0
	v_add_f32_e32 v239, 1.0, v238
	v_div_scale_f32 v240, s[2:3], v239, v239, v36
	v_rcp_f32_e32 v241, v240
	v_div_scale_f32 v242, vcc, v36, v239, v36
	v_fma_f32 v243, -v240, v241, 1.0
	v_fmac_f32_e32 v241, v243, v241
	v_mul_f32_e32 v244, v242, v241
	v_fma_f32 v243, -v240, v244, v242
	v_fmac_f32_e32 v244, v243, v241
	v_fma_f32 v240, -v240, v244, v242
	v_div_fmas_f32 v240, v240, v241, v244
	v_div_fixup_f32 v240, v240, v239, v36
	v_mul_f32_e32 v240, v44, v240
	v_med3_f32 v240, v240, s57, v194
	v_cvt_f16_f32_e32 v246, v240
	global_store_short v237, v245, s[100:101]
	global_store_short v237, v246, s[100:101] offset:32
	s_add_u32 s100, s98, 0x2d600
	s_addc_u32 s101, s99, 0
	v_mul_f32_e32 v238, 0xbfb8aa3b, v33
	v_exp_f32_e32 v238, v238
	s_nop 0
	v_add_f32_e32 v239, 1.0, v238
	v_div_scale_f32 v240, s[2:3], v239, v239, v33
	v_rcp_f32_e32 v241, v240
	v_div_scale_f32 v242, vcc, v33, v239, v33
	v_fma_f32 v243, -v240, v241, 1.0
	v_fmac_f32_e32 v241, v243, v241
	v_mul_f32_e32 v244, v242, v241
	v_fma_f32 v243, -v240, v244, v242
	v_fmac_f32_e32 v244, v243, v241
	v_fma_f32 v240, -v240, v244, v242
	v_div_fmas_f32 v240, v240, v241, v244
	v_div_fixup_f32 v240, v240, v239, v33
	v_mul_f32_e32 v240, v41, v240
	v_med3_f32 v240, v240, s57, v194
	v_cvt_f16_f32_e32 v245, v240
	v_mul_f32_e32 v238, 0xbfb8aa3b, v37
	v_exp_f32_e32 v238, v238
	s_nop 0
	v_add_f32_e32 v239, 1.0, v238
	v_div_scale_f32 v240, s[2:3], v239, v239, v37
	v_rcp_f32_e32 v241, v240
	v_div_scale_f32 v242, vcc, v37, v239, v37
	v_fma_f32 v243, -v240, v241, 1.0
	v_fmac_f32_e32 v241, v243, v241
	v_mul_f32_e32 v244, v242, v241
	v_fma_f32 v243, -v240, v244, v242
	v_fmac_f32_e32 v244, v243, v241
	v_fma_f32 v240, -v240, v244, v242
	v_div_fmas_f32 v240, v240, v241, v244
	v_div_fixup_f32 v240, v240, v239, v37
	v_mul_f32_e32 v240, v45, v240
	v_med3_f32 v240, v240, s57, v194
	v_cvt_f16_f32_e32 v246, v240
	global_store_short v237, v245, s[100:101]
	global_store_short v237, v246, s[100:101] offset:32
	s_add_u32 s100, s98, 0x2ec00
	s_addc_u32 s101, s99, 0
	v_mul_f32_e32 v238, 0xbfb8aa3b, v34
	v_exp_f32_e32 v238, v238
	s_nop 0
	v_add_f32_e32 v239, 1.0, v238
	v_div_scale_f32 v240, s[2:3], v239, v239, v34
	v_rcp_f32_e32 v241, v240
	v_div_scale_f32 v242, vcc, v34, v239, v34
	v_fma_f32 v243, -v240, v241, 1.0
	v_fmac_f32_e32 v241, v243, v241
	v_mul_f32_e32 v244, v242, v241
	v_fma_f32 v243, -v240, v244, v242
	v_fmac_f32_e32 v244, v243, v241
	v_fma_f32 v240, -v240, v244, v242
	v_div_fmas_f32 v240, v240, v241, v244
	v_div_fixup_f32 v240, v240, v239, v34
	v_mul_f32_e32 v240, v42, v240
	v_med3_f32 v240, v240, s57, v194
	v_cvt_f16_f32_e32 v245, v240
	v_mul_f32_e32 v238, 0xbfb8aa3b, v38
	v_exp_f32_e32 v238, v238
	s_nop 0
	v_add_f32_e32 v239, 1.0, v238
	v_div_scale_f32 v240, s[2:3], v239, v239, v38
	v_rcp_f32_e32 v241, v240
	v_div_scale_f32 v242, vcc, v38, v239, v38
	v_fma_f32 v243, -v240, v241, 1.0
	v_fmac_f32_e32 v241, v243, v241
	v_mul_f32_e32 v244, v242, v241
	v_fma_f32 v243, -v240, v244, v242
	v_fmac_f32_e32 v244, v243, v241
	v_fma_f32 v240, -v240, v244, v242
	v_div_fmas_f32 v240, v240, v241, v244
	v_div_fixup_f32 v240, v240, v239, v38
	v_mul_f32_e32 v240, v46, v240
	v_med3_f32 v240, v240, s57, v194
	v_cvt_f16_f32_e32 v246, v240
	global_store_short v237, v245, s[100:101]
	global_store_short v237, v246, s[100:101] offset:32
	s_add_u32 s100, s98, 0x30200
	s_addc_u32 s101, s99, 0
	v_mul_f32_e32 v238, 0xbfb8aa3b, v35
	v_exp_f32_e32 v238, v238
	s_nop 0
	v_add_f32_e32 v239, 1.0, v238
	v_div_scale_f32 v240, s[2:3], v239, v239, v35
	v_rcp_f32_e32 v241, v240
	v_div_scale_f32 v242, vcc, v35, v239, v35
	v_fma_f32 v243, -v240, v241, 1.0
	v_fmac_f32_e32 v241, v243, v241
	v_mul_f32_e32 v244, v242, v241
	v_fma_f32 v243, -v240, v244, v242
	v_fmac_f32_e32 v244, v243, v241
	v_fma_f32 v240, -v240, v244, v242
	v_div_fmas_f32 v240, v240, v241, v244
	v_div_fixup_f32 v240, v240, v239, v35
	v_mul_f32_e32 v240, v43, v240
	v_med3_f32 v240, v240, s57, v194
	v_cvt_f16_f32_e32 v245, v240
	v_mul_f32_e32 v238, 0xbfb8aa3b, v39
	v_exp_f32_e32 v238, v238
	s_nop 0
	v_add_f32_e32 v239, 1.0, v238
	v_div_scale_f32 v240, s[2:3], v239, v239, v39
	v_rcp_f32_e32 v241, v240
	v_div_scale_f32 v242, vcc, v39, v239, v39
	v_fma_f32 v243, -v240, v241, 1.0
	v_fmac_f32_e32 v241, v243, v241
	v_mul_f32_e32 v244, v242, v241
	v_fma_f32 v243, -v240, v244, v242
	v_fmac_f32_e32 v244, v243, v241
	v_fma_f32 v240, -v240, v244, v242
	v_div_fmas_f32 v240, v240, v241, v244
	v_div_fixup_f32 v240, v240, v239, v39
	v_mul_f32_e32 v240, v47, v240
	v_med3_f32 v240, v240, s57, v194
	v_cvt_f16_f32_e32 v246, v240
	global_store_short v237, v245, s[100:101]
	global_store_short v237, v246, s[100:101] offset:32
	s_add_u32 s100, s98, 0x42000
	s_addc_u32 s101, s99, 0
	v_mul_f32_e32 v238, 0xbfb8aa3b, v48
	v_exp_f32_e32 v238, v238
	s_nop 0
	v_add_f32_e32 v239, 1.0, v238
	v_div_scale_f32 v240, s[2:3], v239, v239, v48
	v_rcp_f32_e32 v241, v240
	v_div_scale_f32 v242, vcc, v48, v239, v48
	v_fma_f32 v243, -v240, v241, 1.0
	v_fmac_f32_e32 v241, v243, v241
	v_mul_f32_e32 v244, v242, v241
	v_fma_f32 v243, -v240, v244, v242
	v_fmac_f32_e32 v244, v243, v241
	v_fma_f32 v240, -v240, v244, v242
	v_div_fmas_f32 v240, v240, v241, v244
	v_div_fixup_f32 v240, v240, v239, v48
	v_mul_f32_e32 v240, v56, v240
	v_med3_f32 v240, v240, s57, v194
	v_cvt_f16_f32_e32 v245, v240
	v_mul_f32_e32 v238, 0xbfb8aa3b, v52
	v_exp_f32_e32 v238, v238
	s_nop 0
	v_add_f32_e32 v239, 1.0, v238
	v_div_scale_f32 v240, s[2:3], v239, v239, v52
	v_rcp_f32_e32 v241, v240
	v_div_scale_f32 v242, vcc, v52, v239, v52
	v_fma_f32 v243, -v240, v241, 1.0
	v_fmac_f32_e32 v241, v243, v241
	v_mul_f32_e32 v244, v242, v241
	v_fma_f32 v243, -v240, v244, v242
	v_fmac_f32_e32 v244, v243, v241
	v_fma_f32 v240, -v240, v244, v242
	v_div_fmas_f32 v240, v240, v241, v244
	v_div_fixup_f32 v240, v240, v239, v52
	v_mul_f32_e32 v240, v60, v240
	v_med3_f32 v240, v240, s57, v194
	v_cvt_f16_f32_e32 v246, v240
	global_store_short v237, v245, s[100:101]
	global_store_short v237, v246, s[100:101] offset:32
	s_add_u32 s100, s98, 0x43600
	s_addc_u32 s101, s99, 0
	v_mul_f32_e32 v238, 0xbfb8aa3b, v49
	v_exp_f32_e32 v238, v238
	s_nop 0
	v_add_f32_e32 v239, 1.0, v238
	v_div_scale_f32 v240, s[2:3], v239, v239, v49
	v_rcp_f32_e32 v241, v240
	v_div_scale_f32 v242, vcc, v49, v239, v49
	v_fma_f32 v243, -v240, v241, 1.0
	v_fmac_f32_e32 v241, v243, v241
	v_mul_f32_e32 v244, v242, v241
	v_fma_f32 v243, -v240, v244, v242
	v_fmac_f32_e32 v244, v243, v241
	v_fma_f32 v240, -v240, v244, v242
	v_div_fmas_f32 v240, v240, v241, v244
	v_div_fixup_f32 v240, v240, v239, v49
	v_mul_f32_e32 v240, v57, v240
	v_med3_f32 v240, v240, s57, v194
	v_cvt_f16_f32_e32 v245, v240
	v_mul_f32_e32 v238, 0xbfb8aa3b, v53
	v_exp_f32_e32 v238, v238
	s_nop 0
	v_add_f32_e32 v239, 1.0, v238
	v_div_scale_f32 v240, s[2:3], v239, v239, v53
	v_rcp_f32_e32 v241, v240
	v_div_scale_f32 v242, vcc, v53, v239, v53
	v_fma_f32 v243, -v240, v241, 1.0
	v_fmac_f32_e32 v241, v243, v241
	v_mul_f32_e32 v244, v242, v241
	v_fma_f32 v243, -v240, v244, v242
	v_fmac_f32_e32 v244, v243, v241
	v_fma_f32 v240, -v240, v244, v242
	v_div_fmas_f32 v240, v240, v241, v244
	v_div_fixup_f32 v240, v240, v239, v53
	v_mul_f32_e32 v240, v61, v240
	v_med3_f32 v240, v240, s57, v194
	v_cvt_f16_f32_e32 v246, v240
	global_store_short v237, v245, s[100:101]
	global_store_short v237, v246, s[100:101] offset:32
	s_add_u32 s100, s98, 0x44c00
	s_addc_u32 s101, s99, 0
	v_mul_f32_e32 v238, 0xbfb8aa3b, v50
	v_exp_f32_e32 v238, v238
	s_nop 0
	v_add_f32_e32 v239, 1.0, v238
	v_div_scale_f32 v240, s[2:3], v239, v239, v50
	v_rcp_f32_e32 v241, v240
	v_div_scale_f32 v242, vcc, v50, v239, v50
	v_fma_f32 v243, -v240, v241, 1.0
	v_fmac_f32_e32 v241, v243, v241
	v_mul_f32_e32 v244, v242, v241
	v_fma_f32 v243, -v240, v244, v242
	v_fmac_f32_e32 v244, v243, v241
	v_fma_f32 v240, -v240, v244, v242
	v_div_fmas_f32 v240, v240, v241, v244
	v_div_fixup_f32 v240, v240, v239, v50
	v_mul_f32_e32 v240, v58, v240
	v_med3_f32 v240, v240, s57, v194
	v_cvt_f16_f32_e32 v245, v240
	v_mul_f32_e32 v238, 0xbfb8aa3b, v54
	v_exp_f32_e32 v238, v238
	s_nop 0
	v_add_f32_e32 v239, 1.0, v238
	v_div_scale_f32 v240, s[2:3], v239, v239, v54
	v_rcp_f32_e32 v241, v240
	v_div_scale_f32 v242, vcc, v54, v239, v54
	v_fma_f32 v243, -v240, v241, 1.0
	v_fmac_f32_e32 v241, v243, v241
	v_mul_f32_e32 v244, v242, v241
	v_fma_f32 v243, -v240, v244, v242
	v_fmac_f32_e32 v244, v243, v241
	v_fma_f32 v240, -v240, v244, v242
	v_div_fmas_f32 v240, v240, v241, v244
	v_div_fixup_f32 v240, v240, v239, v54
	v_mul_f32_e32 v240, v62, v240
	v_med3_f32 v240, v240, s57, v194
	v_cvt_f16_f32_e32 v246, v240
	global_store_short v237, v245, s[100:101]
	global_store_short v237, v246, s[100:101] offset:32
	s_add_u32 s100, s98, 0x46200
	s_addc_u32 s101, s99, 0
	v_mul_f32_e32 v238, 0xbfb8aa3b, v51
	v_exp_f32_e32 v238, v238
	s_nop 0
	v_add_f32_e32 v239, 1.0, v238
	v_div_scale_f32 v240, s[2:3], v239, v239, v51
	v_rcp_f32_e32 v241, v240
	v_div_scale_f32 v242, vcc, v51, v239, v51
	v_fma_f32 v243, -v240, v241, 1.0
	v_fmac_f32_e32 v241, v243, v241
	v_mul_f32_e32 v244, v242, v241
	v_fma_f32 v243, -v240, v244, v242
	v_fmac_f32_e32 v244, v243, v241
	v_fma_f32 v240, -v240, v244, v242
	v_div_fmas_f32 v240, v240, v241, v244
	v_div_fixup_f32 v240, v240, v239, v51
	v_mul_f32_e32 v240, v59, v240
	v_med3_f32 v240, v240, s57, v194
	v_cvt_f16_f32_e32 v245, v240
	v_mul_f32_e32 v238, 0xbfb8aa3b, v55
	v_exp_f32_e32 v238, v238
	s_nop 0
	v_add_f32_e32 v239, 1.0, v238
	v_div_scale_f32 v240, s[2:3], v239, v239, v55
	v_rcp_f32_e32 v241, v240
	v_div_scale_f32 v242, vcc, v55, v239, v55
	v_fma_f32 v243, -v240, v241, 1.0
	v_fmac_f32_e32 v241, v243, v241
	v_mul_f32_e32 v244, v242, v241
	v_fma_f32 v243, -v240, v244, v242
	v_fmac_f32_e32 v244, v243, v241
	v_fma_f32 v240, -v240, v244, v242
	v_div_fmas_f32 v240, v240, v241, v244
	v_div_fixup_f32 v240, v240, v239, v55
	v_mul_f32_e32 v240, v63, v240
	v_med3_f32 v240, v240, s57, v194
	v_cvt_f16_f32_e32 v246, v240
	global_store_short v237, v245, s[100:101]
	global_store_short v237, v246, s[100:101] offset:32
	s_add_u32 s100, s98, 0x58000
	s_addc_u32 s101, s99, 0
	v_mul_f32_e32 v238, 0xbfb8aa3b, v64
	v_exp_f32_e32 v238, v238
	s_nop 0
	v_add_f32_e32 v239, 1.0, v238
	v_div_scale_f32 v240, s[2:3], v239, v239, v64
	v_rcp_f32_e32 v241, v240
	v_div_scale_f32 v242, vcc, v64, v239, v64
	v_fma_f32 v243, -v240, v241, 1.0
	v_fmac_f32_e32 v241, v243, v241
	v_mul_f32_e32 v244, v242, v241
	v_fma_f32 v243, -v240, v244, v242
	v_fmac_f32_e32 v244, v243, v241
	v_fma_f32 v240, -v240, v244, v242
	v_div_fmas_f32 v240, v240, v241, v244
	v_div_fixup_f32 v240, v240, v239, v64
	v_mul_f32_e32 v240, v72, v240
	v_med3_f32 v240, v240, s57, v194
	v_cvt_f16_f32_e32 v245, v240
	v_mul_f32_e32 v238, 0xbfb8aa3b, v68
	v_exp_f32_e32 v238, v238
	s_nop 0
	v_add_f32_e32 v239, 1.0, v238
	v_div_scale_f32 v240, s[2:3], v239, v239, v68
	v_rcp_f32_e32 v241, v240
	v_div_scale_f32 v242, vcc, v68, v239, v68
	v_fma_f32 v243, -v240, v241, 1.0
	v_fmac_f32_e32 v241, v243, v241
	v_mul_f32_e32 v244, v242, v241
	v_fma_f32 v243, -v240, v244, v242
	v_fmac_f32_e32 v244, v243, v241
	v_fma_f32 v240, -v240, v244, v242
	v_div_fmas_f32 v240, v240, v241, v244
	v_div_fixup_f32 v240, v240, v239, v68
	v_mul_f32_e32 v240, v76, v240
	v_med3_f32 v240, v240, s57, v194
	v_cvt_f16_f32_e32 v246, v240
	global_store_short v237, v245, s[100:101]
	global_store_short v237, v246, s[100:101] offset:32
	s_add_u32 s100, s98, 0x59600
	s_addc_u32 s101, s99, 0
	v_mul_f32_e32 v238, 0xbfb8aa3b, v65
	v_exp_f32_e32 v238, v238
	s_nop 0
	v_add_f32_e32 v239, 1.0, v238
	v_div_scale_f32 v240, s[2:3], v239, v239, v65
	v_rcp_f32_e32 v241, v240
	v_div_scale_f32 v242, vcc, v65, v239, v65
	v_fma_f32 v243, -v240, v241, 1.0
	v_fmac_f32_e32 v241, v243, v241
	v_mul_f32_e32 v244, v242, v241
	v_fma_f32 v243, -v240, v244, v242
	v_fmac_f32_e32 v244, v243, v241
	v_fma_f32 v240, -v240, v244, v242
	v_div_fmas_f32 v240, v240, v241, v244
	v_div_fixup_f32 v240, v240, v239, v65
	v_mul_f32_e32 v240, v73, v240
	v_med3_f32 v240, v240, s57, v194
	v_cvt_f16_f32_e32 v245, v240
	v_mul_f32_e32 v238, 0xbfb8aa3b, v69
	v_exp_f32_e32 v238, v238
	s_nop 0
	v_add_f32_e32 v239, 1.0, v238
	v_div_scale_f32 v240, s[2:3], v239, v239, v69
	v_rcp_f32_e32 v241, v240
	v_div_scale_f32 v242, vcc, v69, v239, v69
	v_fma_f32 v243, -v240, v241, 1.0
	v_fmac_f32_e32 v241, v243, v241
	v_mul_f32_e32 v244, v242, v241
	v_fma_f32 v243, -v240, v244, v242
	v_fmac_f32_e32 v244, v243, v241
	v_fma_f32 v240, -v240, v244, v242
	v_div_fmas_f32 v240, v240, v241, v244
	v_div_fixup_f32 v240, v240, v239, v69
	v_mul_f32_e32 v240, v77, v240
	v_med3_f32 v240, v240, s57, v194
	v_cvt_f16_f32_e32 v246, v240
	global_store_short v237, v245, s[100:101]
	global_store_short v237, v246, s[100:101] offset:32
	s_add_u32 s100, s98, 0x5ac00
	s_addc_u32 s101, s99, 0
	v_mul_f32_e32 v238, 0xbfb8aa3b, v66
	v_exp_f32_e32 v238, v238
	s_nop 0
	v_add_f32_e32 v239, 1.0, v238
	v_div_scale_f32 v240, s[2:3], v239, v239, v66
	v_rcp_f32_e32 v241, v240
	v_div_scale_f32 v242, vcc, v66, v239, v66
	v_fma_f32 v243, -v240, v241, 1.0
	v_fmac_f32_e32 v241, v243, v241
	v_mul_f32_e32 v244, v242, v241
	v_fma_f32 v243, -v240, v244, v242
	v_fmac_f32_e32 v244, v243, v241
	v_fma_f32 v240, -v240, v244, v242
	v_div_fmas_f32 v240, v240, v241, v244
	v_div_fixup_f32 v240, v240, v239, v66
	v_mul_f32_e32 v240, v74, v240
	v_med3_f32 v240, v240, s57, v194
	v_cvt_f16_f32_e32 v245, v240
	v_mul_f32_e32 v238, 0xbfb8aa3b, v70
	v_exp_f32_e32 v238, v238
	s_nop 0
	v_add_f32_e32 v239, 1.0, v238
	v_div_scale_f32 v240, s[2:3], v239, v239, v70
	v_rcp_f32_e32 v241, v240
	v_div_scale_f32 v242, vcc, v70, v239, v70
	v_fma_f32 v243, -v240, v241, 1.0
	v_fmac_f32_e32 v241, v243, v241
	v_mul_f32_e32 v244, v242, v241
	v_fma_f32 v243, -v240, v244, v242
	v_fmac_f32_e32 v244, v243, v241
	v_fma_f32 v240, -v240, v244, v242
	v_div_fmas_f32 v240, v240, v241, v244
	v_div_fixup_f32 v240, v240, v239, v70
	v_mul_f32_e32 v240, v78, v240
	v_med3_f32 v240, v240, s57, v194
	v_cvt_f16_f32_e32 v246, v240
	global_store_short v237, v245, s[100:101]
	global_store_short v237, v246, s[100:101] offset:32
	s_add_u32 s100, s98, 0x5c200
	s_addc_u32 s101, s99, 0
	v_mul_f32_e32 v238, 0xbfb8aa3b, v67
	v_exp_f32_e32 v238, v238
	s_nop 0
	v_add_f32_e32 v239, 1.0, v238
	v_div_scale_f32 v240, s[2:3], v239, v239, v67
	v_rcp_f32_e32 v241, v240
	v_div_scale_f32 v242, vcc, v67, v239, v67
	v_fma_f32 v243, -v240, v241, 1.0
	v_fmac_f32_e32 v241, v243, v241
	v_mul_f32_e32 v244, v242, v241
	v_fma_f32 v243, -v240, v244, v242
	v_fmac_f32_e32 v244, v243, v241
	v_fma_f32 v240, -v240, v244, v242
	v_div_fmas_f32 v240, v240, v241, v244
	v_div_fixup_f32 v240, v240, v239, v67
	v_mul_f32_e32 v240, v75, v240
	v_med3_f32 v240, v240, s57, v194
	v_cvt_f16_f32_e32 v245, v240
	v_mul_f32_e32 v238, 0xbfb8aa3b, v71
	v_exp_f32_e32 v238, v238
	s_nop 0
	v_add_f32_e32 v239, 1.0, v238
	v_div_scale_f32 v240, s[2:3], v239, v239, v71
	v_rcp_f32_e32 v241, v240
	v_div_scale_f32 v242, vcc, v71, v239, v71
	v_fma_f32 v243, -v240, v241, 1.0
	v_fmac_f32_e32 v241, v243, v241
	v_mul_f32_e32 v244, v242, v241
	v_fma_f32 v243, -v240, v244, v242
	v_fmac_f32_e32 v244, v243, v241
	v_fma_f32 v240, -v240, v244, v242
	v_div_fmas_f32 v240, v240, v241, v244
	v_div_fixup_f32 v240, v240, v239, v71
	v_mul_f32_e32 v240, v79, v240
	v_med3_f32 v240, v240, s57, v194
	v_cvt_f16_f32_e32 v246, v240
	global_store_short v237, v245, s[100:101]
	global_store_short v237, v246, s[100:101] offset:32
	s_add_u32 s100, s98, 0x6e000
	s_addc_u32 s101, s99, 0
	v_mul_f32_e32 v238, 0xbfb8aa3b, v80
	v_exp_f32_e32 v238, v238
	s_nop 0
	v_add_f32_e32 v239, 1.0, v238
	v_div_scale_f32 v240, s[2:3], v239, v239, v80
	v_rcp_f32_e32 v241, v240
	v_div_scale_f32 v242, vcc, v80, v239, v80
	v_fma_f32 v243, -v240, v241, 1.0
	v_fmac_f32_e32 v241, v243, v241
	v_mul_f32_e32 v244, v242, v241
	v_fma_f32 v243, -v240, v244, v242
	v_fmac_f32_e32 v244, v243, v241
	v_fma_f32 v240, -v240, v244, v242
	v_div_fmas_f32 v240, v240, v241, v244
	v_div_fixup_f32 v240, v240, v239, v80
	v_mul_f32_e32 v240, v88, v240
	v_med3_f32 v240, v240, s57, v194
	v_cvt_f16_f32_e32 v245, v240
	v_mul_f32_e32 v238, 0xbfb8aa3b, v84
	v_exp_f32_e32 v238, v238
	s_nop 0
	v_add_f32_e32 v239, 1.0, v238
	v_div_scale_f32 v240, s[2:3], v239, v239, v84
	v_rcp_f32_e32 v241, v240
	v_div_scale_f32 v242, vcc, v84, v239, v84
	v_fma_f32 v243, -v240, v241, 1.0
	v_fmac_f32_e32 v241, v243, v241
	v_mul_f32_e32 v244, v242, v241
	v_fma_f32 v243, -v240, v244, v242
	v_fmac_f32_e32 v244, v243, v241
	v_fma_f32 v240, -v240, v244, v242
	v_div_fmas_f32 v240, v240, v241, v244
	v_div_fixup_f32 v240, v240, v239, v84
	v_mul_f32_e32 v240, v92, v240
	v_med3_f32 v240, v240, s57, v194
	v_cvt_f16_f32_e32 v246, v240
	global_store_short v237, v245, s[100:101]
	global_store_short v237, v246, s[100:101] offset:32
	s_add_u32 s100, s98, 0x6f600
	s_addc_u32 s101, s99, 0
	v_mul_f32_e32 v238, 0xbfb8aa3b, v81
	v_exp_f32_e32 v238, v238
	s_nop 0
	v_add_f32_e32 v239, 1.0, v238
	v_div_scale_f32 v240, s[2:3], v239, v239, v81
	v_rcp_f32_e32 v241, v240
	v_div_scale_f32 v242, vcc, v81, v239, v81
	v_fma_f32 v243, -v240, v241, 1.0
	v_fmac_f32_e32 v241, v243, v241
	v_mul_f32_e32 v244, v242, v241
	v_fma_f32 v243, -v240, v244, v242
	v_fmac_f32_e32 v244, v243, v241
	v_fma_f32 v240, -v240, v244, v242
	v_div_fmas_f32 v240, v240, v241, v244
	v_div_fixup_f32 v240, v240, v239, v81
	v_mul_f32_e32 v240, v89, v240
	v_med3_f32 v240, v240, s57, v194
	v_cvt_f16_f32_e32 v245, v240
	v_mul_f32_e32 v238, 0xbfb8aa3b, v85
	v_exp_f32_e32 v238, v238
	s_nop 0
	v_add_f32_e32 v239, 1.0, v238
	v_div_scale_f32 v240, s[2:3], v239, v239, v85
	v_rcp_f32_e32 v241, v240
	v_div_scale_f32 v242, vcc, v85, v239, v85
	v_fma_f32 v243, -v240, v241, 1.0
	v_fmac_f32_e32 v241, v243, v241
	v_mul_f32_e32 v244, v242, v241
	v_fma_f32 v243, -v240, v244, v242
	v_fmac_f32_e32 v244, v243, v241
	v_fma_f32 v240, -v240, v244, v242
	v_div_fmas_f32 v240, v240, v241, v244
	v_div_fixup_f32 v240, v240, v239, v85
	v_mul_f32_e32 v240, v93, v240
	v_med3_f32 v240, v240, s57, v194
	v_cvt_f16_f32_e32 v246, v240
	global_store_short v237, v245, s[100:101]
	global_store_short v237, v246, s[100:101] offset:32
	s_add_u32 s100, s98, 0x70c00
	s_addc_u32 s101, s99, 0
	v_mul_f32_e32 v238, 0xbfb8aa3b, v82
	v_exp_f32_e32 v238, v238
	s_nop 0
	v_add_f32_e32 v239, 1.0, v238
	v_div_scale_f32 v240, s[2:3], v239, v239, v82
	v_rcp_f32_e32 v241, v240
	v_div_scale_f32 v242, vcc, v82, v239, v82
	v_fma_f32 v243, -v240, v241, 1.0
	v_fmac_f32_e32 v241, v243, v241
	v_mul_f32_e32 v244, v242, v241
	v_fma_f32 v243, -v240, v244, v242
	v_fmac_f32_e32 v244, v243, v241
	v_fma_f32 v240, -v240, v244, v242
	v_div_fmas_f32 v240, v240, v241, v244
	v_div_fixup_f32 v240, v240, v239, v82
	v_mul_f32_e32 v240, v90, v240
	v_med3_f32 v240, v240, s57, v194
	v_cvt_f16_f32_e32 v245, v240
	v_mul_f32_e32 v238, 0xbfb8aa3b, v86
	v_exp_f32_e32 v238, v238
	s_nop 0
	v_add_f32_e32 v239, 1.0, v238
	v_div_scale_f32 v240, s[2:3], v239, v239, v86
	v_rcp_f32_e32 v241, v240
	v_div_scale_f32 v242, vcc, v86, v239, v86
	v_fma_f32 v243, -v240, v241, 1.0
	v_fmac_f32_e32 v241, v243, v241
	v_mul_f32_e32 v244, v242, v241
	v_fma_f32 v243, -v240, v244, v242
	v_fmac_f32_e32 v244, v243, v241
	v_fma_f32 v240, -v240, v244, v242
	v_div_fmas_f32 v240, v240, v241, v244
	v_div_fixup_f32 v240, v240, v239, v86
	v_mul_f32_e32 v240, v94, v240
	v_med3_f32 v240, v240, s57, v194
	v_cvt_f16_f32_e32 v246, v240
	global_store_short v237, v245, s[100:101]
	global_store_short v237, v246, s[100:101] offset:32
	s_add_u32 s100, s98, 0x72200
	s_addc_u32 s101, s99, 0
	v_mul_f32_e32 v238, 0xbfb8aa3b, v83
	v_exp_f32_e32 v238, v238
	s_nop 0
	v_add_f32_e32 v239, 1.0, v238
	v_div_scale_f32 v240, s[2:3], v239, v239, v83
	v_rcp_f32_e32 v241, v240
	v_div_scale_f32 v242, vcc, v83, v239, v83
	v_fma_f32 v243, -v240, v241, 1.0
	v_fmac_f32_e32 v241, v243, v241
	v_mul_f32_e32 v244, v242, v241
	v_fma_f32 v243, -v240, v244, v242
	v_fmac_f32_e32 v244, v243, v241
	v_fma_f32 v240, -v240, v244, v242
	v_div_fmas_f32 v240, v240, v241, v244
	v_div_fixup_f32 v240, v240, v239, v83
	v_mul_f32_e32 v240, v91, v240
	v_med3_f32 v240, v240, s57, v194
	v_cvt_f16_f32_e32 v245, v240
	v_mul_f32_e32 v238, 0xbfb8aa3b, v87
	v_exp_f32_e32 v238, v238
	s_nop 0
	v_add_f32_e32 v239, 1.0, v238
	v_div_scale_f32 v240, s[2:3], v239, v239, v87
	v_rcp_f32_e32 v241, v240
	v_div_scale_f32 v242, vcc, v87, v239, v87
	v_fma_f32 v243, -v240, v241, 1.0
	v_fmac_f32_e32 v241, v243, v241
	v_mul_f32_e32 v244, v242, v241
	v_fma_f32 v243, -v240, v244, v242
	v_fmac_f32_e32 v244, v243, v241
	v_fma_f32 v240, -v240, v244, v242
	v_div_fmas_f32 v240, v240, v241, v244
	v_div_fixup_f32 v240, v240, v239, v87
	v_mul_f32_e32 v240, v95, v240
	v_med3_f32 v240, v240, s57, v194
	v_cvt_f16_f32_e32 v246, v240
	global_store_short v237, v245, s[100:101]
	global_store_short v237, v246, s[100:101] offset:32
	s_add_u32 s100, s98, 0x84000
	s_addc_u32 s101, s99, 0
	v_mul_f32_e32 v238, 0xbfb8aa3b, v96
	v_exp_f32_e32 v238, v238
	s_nop 0
	v_add_f32_e32 v239, 1.0, v238
	v_div_scale_f32 v240, s[2:3], v239, v239, v96
	v_rcp_f32_e32 v241, v240
	v_div_scale_f32 v242, vcc, v96, v239, v96
	v_fma_f32 v243, -v240, v241, 1.0
	v_fmac_f32_e32 v241, v243, v241
	v_mul_f32_e32 v244, v242, v241
	v_fma_f32 v243, -v240, v244, v242
	v_fmac_f32_e32 v244, v243, v241
	v_fma_f32 v240, -v240, v244, v242
	v_div_fmas_f32 v240, v240, v241, v244
	v_div_fixup_f32 v240, v240, v239, v96
	v_mul_f32_e32 v240, v104, v240
	v_med3_f32 v240, v240, s57, v194
	v_cvt_f16_f32_e32 v245, v240
	v_mul_f32_e32 v238, 0xbfb8aa3b, v100
	v_exp_f32_e32 v238, v238
	s_nop 0
	v_add_f32_e32 v239, 1.0, v238
	v_div_scale_f32 v240, s[2:3], v239, v239, v100
	v_rcp_f32_e32 v241, v240
	v_div_scale_f32 v242, vcc, v100, v239, v100
	v_fma_f32 v243, -v240, v241, 1.0
	v_fmac_f32_e32 v241, v243, v241
	v_mul_f32_e32 v244, v242, v241
	v_fma_f32 v243, -v240, v244, v242
	v_fmac_f32_e32 v244, v243, v241
	v_fma_f32 v240, -v240, v244, v242
	v_div_fmas_f32 v240, v240, v241, v244
	v_div_fixup_f32 v240, v240, v239, v100
	v_mul_f32_e32 v240, v108, v240
	v_med3_f32 v240, v240, s57, v194
	v_cvt_f16_f32_e32 v246, v240
	global_store_short v237, v245, s[100:101]
	global_store_short v237, v246, s[100:101] offset:32
	s_add_u32 s100, s98, 0x85600
	s_addc_u32 s101, s99, 0
	v_mul_f32_e32 v238, 0xbfb8aa3b, v97
	v_exp_f32_e32 v238, v238
	s_nop 0
	v_add_f32_e32 v239, 1.0, v238
	v_div_scale_f32 v240, s[2:3], v239, v239, v97
	v_rcp_f32_e32 v241, v240
	v_div_scale_f32 v242, vcc, v97, v239, v97
	v_fma_f32 v243, -v240, v241, 1.0
	v_fmac_f32_e32 v241, v243, v241
	v_mul_f32_e32 v244, v242, v241
	v_fma_f32 v243, -v240, v244, v242
	v_fmac_f32_e32 v244, v243, v241
	v_fma_f32 v240, -v240, v244, v242
	v_div_fmas_f32 v240, v240, v241, v244
	v_div_fixup_f32 v240, v240, v239, v97
	v_mul_f32_e32 v240, v105, v240
	v_med3_f32 v240, v240, s57, v194
	v_cvt_f16_f32_e32 v245, v240
	v_mul_f32_e32 v238, 0xbfb8aa3b, v101
	v_exp_f32_e32 v238, v238
	s_nop 0
	v_add_f32_e32 v239, 1.0, v238
	v_div_scale_f32 v240, s[2:3], v239, v239, v101
	v_rcp_f32_e32 v241, v240
	v_div_scale_f32 v242, vcc, v101, v239, v101
	v_fma_f32 v243, -v240, v241, 1.0
	v_fmac_f32_e32 v241, v243, v241
	v_mul_f32_e32 v244, v242, v241
	v_fma_f32 v243, -v240, v244, v242
	v_fmac_f32_e32 v244, v243, v241
	v_fma_f32 v240, -v240, v244, v242
	v_div_fmas_f32 v240, v240, v241, v244
	v_div_fixup_f32 v240, v240, v239, v101
	v_mul_f32_e32 v240, v109, v240
	v_med3_f32 v240, v240, s57, v194
	v_cvt_f16_f32_e32 v246, v240
	global_store_short v237, v245, s[100:101]
	global_store_short v237, v246, s[100:101] offset:32
	s_add_u32 s100, s98, 0x86c00
	s_addc_u32 s101, s99, 0
	v_mul_f32_e32 v238, 0xbfb8aa3b, v98
	v_exp_f32_e32 v238, v238
	s_nop 0
	v_add_f32_e32 v239, 1.0, v238
	v_div_scale_f32 v240, s[2:3], v239, v239, v98
	v_rcp_f32_e32 v241, v240
	v_div_scale_f32 v242, vcc, v98, v239, v98
	v_fma_f32 v243, -v240, v241, 1.0
	v_fmac_f32_e32 v241, v243, v241
	v_mul_f32_e32 v244, v242, v241
	v_fma_f32 v243, -v240, v244, v242
	v_fmac_f32_e32 v244, v243, v241
	v_fma_f32 v240, -v240, v244, v242
	v_div_fmas_f32 v240, v240, v241, v244
	v_div_fixup_f32 v240, v240, v239, v98
	v_mul_f32_e32 v240, v106, v240
	v_med3_f32 v240, v240, s57, v194
	v_cvt_f16_f32_e32 v245, v240
	v_mul_f32_e32 v238, 0xbfb8aa3b, v102
	v_exp_f32_e32 v238, v238
	s_nop 0
	v_add_f32_e32 v239, 1.0, v238
	v_div_scale_f32 v240, s[2:3], v239, v239, v102
	v_rcp_f32_e32 v241, v240
	v_div_scale_f32 v242, vcc, v102, v239, v102
	v_fma_f32 v243, -v240, v241, 1.0
	v_fmac_f32_e32 v241, v243, v241
	v_mul_f32_e32 v244, v242, v241
	v_fma_f32 v243, -v240, v244, v242
	v_fmac_f32_e32 v244, v243, v241
	v_fma_f32 v240, -v240, v244, v242
	v_div_fmas_f32 v240, v240, v241, v244
	v_div_fixup_f32 v240, v240, v239, v102
	v_mul_f32_e32 v240, v110, v240
	v_med3_f32 v240, v240, s57, v194
	v_cvt_f16_f32_e32 v246, v240
	global_store_short v237, v245, s[100:101]
	global_store_short v237, v246, s[100:101] offset:32
	s_add_u32 s100, s98, 0x88200
	s_addc_u32 s101, s99, 0
	v_mul_f32_e32 v238, 0xbfb8aa3b, v99
	v_exp_f32_e32 v238, v238
	s_nop 0
	v_add_f32_e32 v239, 1.0, v238
	v_div_scale_f32 v240, s[2:3], v239, v239, v99
	v_rcp_f32_e32 v241, v240
	v_div_scale_f32 v242, vcc, v99, v239, v99
	v_fma_f32 v243, -v240, v241, 1.0
	v_fmac_f32_e32 v241, v243, v241
	v_mul_f32_e32 v244, v242, v241
	v_fma_f32 v243, -v240, v244, v242
	v_fmac_f32_e32 v244, v243, v241
	v_fma_f32 v240, -v240, v244, v242
	v_div_fmas_f32 v240, v240, v241, v244
	v_div_fixup_f32 v240, v240, v239, v99
	v_mul_f32_e32 v240, v107, v240
	v_med3_f32 v240, v240, s57, v194
	v_cvt_f16_f32_e32 v245, v240
	v_mul_f32_e32 v238, 0xbfb8aa3b, v103
	v_exp_f32_e32 v238, v238
	s_nop 0
	v_add_f32_e32 v239, 1.0, v238
	v_div_scale_f32 v240, s[2:3], v239, v239, v103
	v_rcp_f32_e32 v241, v240
	v_div_scale_f32 v242, vcc, v103, v239, v103
	v_fma_f32 v243, -v240, v241, 1.0
	v_fmac_f32_e32 v241, v243, v241
	v_mul_f32_e32 v244, v242, v241
	v_fma_f32 v243, -v240, v244, v242
	v_fmac_f32_e32 v244, v243, v241
	v_fma_f32 v240, -v240, v244, v242
	v_div_fmas_f32 v240, v240, v241, v244
	v_div_fixup_f32 v240, v240, v239, v103
	v_mul_f32_e32 v240, v111, v240
	v_med3_f32 v240, v240, s57, v194
	v_cvt_f16_f32_e32 v246, v240
	global_store_short v237, v245, s[100:101]
	global_store_short v237, v246, s[100:101] offset:32
	s_add_u32 s100, s98, 0x9a000
	s_addc_u32 s101, s99, 0
	v_mul_f32_e32 v238, 0xbfb8aa3b, v116
	v_exp_f32_e32 v238, v238
	s_nop 0
	v_add_f32_e32 v239, 1.0, v238
	v_div_scale_f32 v240, s[2:3], v239, v239, v116
	v_rcp_f32_e32 v241, v240
	v_div_scale_f32 v242, vcc, v116, v239, v116
	v_fma_f32 v243, -v240, v241, 1.0
	v_fmac_f32_e32 v241, v243, v241
	v_mul_f32_e32 v244, v242, v241
	v_fma_f32 v243, -v240, v244, v242
	v_fmac_f32_e32 v244, v243, v241
	v_fma_f32 v240, -v240, v244, v242
	v_div_fmas_f32 v240, v240, v241, v244
	v_div_fixup_f32 v240, v240, v239, v116
	v_mul_f32_e32 v240, v124, v240
	v_med3_f32 v240, v240, s57, v194
	v_cvt_f16_f32_e32 v245, v240
	v_mul_f32_e32 v238, 0xbfb8aa3b, v120
	v_exp_f32_e32 v238, v238
	s_nop 0
	v_add_f32_e32 v239, 1.0, v238
	v_div_scale_f32 v240, s[2:3], v239, v239, v120
	v_rcp_f32_e32 v241, v240
	v_div_scale_f32 v242, vcc, v120, v239, v120
	v_fma_f32 v243, -v240, v241, 1.0
	v_fmac_f32_e32 v241, v243, v241
	v_mul_f32_e32 v244, v242, v241
	v_fma_f32 v243, -v240, v244, v242
	v_fmac_f32_e32 v244, v243, v241
	v_fma_f32 v240, -v240, v244, v242
	v_div_fmas_f32 v240, v240, v241, v244
	v_div_fixup_f32 v240, v240, v239, v120
	v_mul_f32_e32 v240, v128, v240
	v_med3_f32 v240, v240, s57, v194
	v_cvt_f16_f32_e32 v246, v240
	global_store_short v237, v245, s[100:101]
	global_store_short v237, v246, s[100:101] offset:32
	s_add_u32 s100, s98, 0x9b600
	s_addc_u32 s101, s99, 0
	v_mul_f32_e32 v238, 0xbfb8aa3b, v117
	v_exp_f32_e32 v238, v238
	s_nop 0
	v_add_f32_e32 v239, 1.0, v238
	v_div_scale_f32 v240, s[2:3], v239, v239, v117
	v_rcp_f32_e32 v241, v240
	v_div_scale_f32 v242, vcc, v117, v239, v117
	v_fma_f32 v243, -v240, v241, 1.0
	v_fmac_f32_e32 v241, v243, v241
	v_mul_f32_e32 v244, v242, v241
	v_fma_f32 v243, -v240, v244, v242
	v_fmac_f32_e32 v244, v243, v241
	v_fma_f32 v240, -v240, v244, v242
	v_div_fmas_f32 v240, v240, v241, v244
	v_div_fixup_f32 v240, v240, v239, v117
	v_mul_f32_e32 v240, v125, v240
	v_med3_f32 v240, v240, s57, v194
	v_cvt_f16_f32_e32 v245, v240
	v_mul_f32_e32 v238, 0xbfb8aa3b, v121
	v_exp_f32_e32 v238, v238
	s_nop 0
	v_add_f32_e32 v239, 1.0, v238
	v_div_scale_f32 v240, s[2:3], v239, v239, v121
	v_rcp_f32_e32 v241, v240
	v_div_scale_f32 v242, vcc, v121, v239, v121
	v_fma_f32 v243, -v240, v241, 1.0
	v_fmac_f32_e32 v241, v243, v241
	v_mul_f32_e32 v244, v242, v241
	v_fma_f32 v243, -v240, v244, v242
	v_fmac_f32_e32 v244, v243, v241
	v_fma_f32 v240, -v240, v244, v242
	v_div_fmas_f32 v240, v240, v241, v244
	v_div_fixup_f32 v240, v240, v239, v121
	v_mul_f32_e32 v240, v129, v240
	v_med3_f32 v240, v240, s57, v194
	v_cvt_f16_f32_e32 v246, v240
	global_store_short v237, v245, s[100:101]
	global_store_short v237, v246, s[100:101] offset:32
	s_add_u32 s100, s98, 0x9cc00
	s_addc_u32 s101, s99, 0
	v_mul_f32_e32 v238, 0xbfb8aa3b, v118
	v_exp_f32_e32 v238, v238
	s_nop 0
	v_add_f32_e32 v239, 1.0, v238
	v_div_scale_f32 v240, s[2:3], v239, v239, v118
	v_rcp_f32_e32 v241, v240
	v_div_scale_f32 v242, vcc, v118, v239, v118
	v_fma_f32 v243, -v240, v241, 1.0
	v_fmac_f32_e32 v241, v243, v241
	v_mul_f32_e32 v244, v242, v241
	v_fma_f32 v243, -v240, v244, v242
	v_fmac_f32_e32 v244, v243, v241
	v_fma_f32 v240, -v240, v244, v242
	v_div_fmas_f32 v240, v240, v241, v244
	v_div_fixup_f32 v240, v240, v239, v118
	v_mul_f32_e32 v240, v126, v240
	v_med3_f32 v240, v240, s57, v194
	v_cvt_f16_f32_e32 v245, v240
	v_mul_f32_e32 v238, 0xbfb8aa3b, v122
	v_exp_f32_e32 v238, v238
	s_nop 0
	v_add_f32_e32 v239, 1.0, v238
	v_div_scale_f32 v240, s[2:3], v239, v239, v122
	v_rcp_f32_e32 v241, v240
	v_div_scale_f32 v242, vcc, v122, v239, v122
	v_fma_f32 v243, -v240, v241, 1.0
	v_fmac_f32_e32 v241, v243, v241
	v_mul_f32_e32 v244, v242, v241
	v_fma_f32 v243, -v240, v244, v242
	v_fmac_f32_e32 v244, v243, v241
	v_fma_f32 v240, -v240, v244, v242
	v_div_fmas_f32 v240, v240, v241, v244
	v_div_fixup_f32 v240, v240, v239, v122
	v_mul_f32_e32 v240, v130, v240
	v_med3_f32 v240, v240, s57, v194
	v_cvt_f16_f32_e32 v246, v240
	global_store_short v237, v245, s[100:101]
	global_store_short v237, v246, s[100:101] offset:32
	s_add_u32 s100, s98, 0x9e200
	s_addc_u32 s101, s99, 0
	v_mul_f32_e32 v238, 0xbfb8aa3b, v119
	v_exp_f32_e32 v238, v238
	s_nop 0
	v_add_f32_e32 v239, 1.0, v238
	v_div_scale_f32 v240, s[2:3], v239, v239, v119
	v_rcp_f32_e32 v241, v240
	v_div_scale_f32 v242, vcc, v119, v239, v119
	v_fma_f32 v243, -v240, v241, 1.0
	v_fmac_f32_e32 v241, v243, v241
	v_mul_f32_e32 v244, v242, v241
	v_fma_f32 v243, -v240, v244, v242
	v_fmac_f32_e32 v244, v243, v241
	v_fma_f32 v240, -v240, v244, v242
	v_div_fmas_f32 v240, v240, v241, v244
	v_div_fixup_f32 v240, v240, v239, v119
	v_mul_f32_e32 v240, v127, v240
	v_med3_f32 v240, v240, s57, v194
	v_cvt_f16_f32_e32 v245, v240
	v_mul_f32_e32 v238, 0xbfb8aa3b, v123
	v_exp_f32_e32 v238, v238
	s_nop 0
	v_add_f32_e32 v239, 1.0, v238
	v_div_scale_f32 v240, s[2:3], v239, v239, v123
	v_rcp_f32_e32 v241, v240
	v_div_scale_f32 v242, vcc, v123, v239, v123
	v_fma_f32 v243, -v240, v241, 1.0
	v_fmac_f32_e32 v241, v243, v241
	v_mul_f32_e32 v244, v242, v241
	v_fma_f32 v243, -v240, v244, v242
	v_fmac_f32_e32 v244, v243, v241
	v_fma_f32 v240, -v240, v244, v242
	v_div_fmas_f32 v240, v240, v241, v244
	v_div_fixup_f32 v240, v240, v239, v123
	v_mul_f32_e32 v240, v131, v240
	v_med3_f32 v240, v240, s57, v194
	v_cvt_f16_f32_e32 v246, v240
	global_store_short v237, v245, s[100:101]
	global_store_short v237, v246, s[100:101] offset:32
	s_add_i32 s10, s10, s60
	s_lshr_b32 s4, s62, 1
	s_cmp_ge_i32 s10, s4
	s_cbranch_scc0 .LBB0_631
